# v46 + store-ack decoupling in streaming phases: norm trip-top vmcnt(0)->(4), second half (4)->(8), SGU unit top (8)->(16)
# speedup vs baseline: 1.0024x; 1.0024x over previous
.LBB0_625:
	s_ashr_i32 s0, s10, 31
	s_lshr_b32 s0, s0, 28
	s_add_i32 s0, s10, s0
	s_ashr_i32 s20, s0, 4
	s_and_b32 s0, s0, -16
	s_waitcnt vmcnt(16)
	s_sub_i32 s6, s10, s0
	s_cmp_eq_u32 s6, s18
	s_cbranch_scc1 .LBB0_629
	s_ashr_i32 s7, s6, 31
	s_lshl_b64 s[0:1], s[6:7], 15
	v_lshl_add_u64 v[86:87], v[120:121], 0, s[0:1]
	s_lshl_b32 s0, s20, 11
	s_sub_i32 s0, s16, s0
	s_ashr_i32 s1, s0, 31
	v_lshl_add_u64 v[88:89], s[0:1], 2, v[122:123]
	s_lshl_b32 s0, s20, 12
	s_sub_i32 s0, s17, s0
	s_ashr_i32 s1, s0, 31
	s_lshl_b64 s[0:1], s[0:1], 2
	v_lshl_add_u64 v[90:91], v[124:125], 0, s[0:1]
	v_lshl_add_u64 v[92:93], v[126:127], 0, s[0:1]
	s_mov_b64 s[0:1], 0x2000
	v_lshl_add_u64 v[94:95], v[86:87], 0, s[0:1]
	s_mov_b64 s[0:1], 0x4000
	v_lshl_add_u64 v[96:97], v[86:87], 0, s[0:1]
	s_mov_b64 s[0:1], 0x6000
	v_lshl_add_u64 v[98:99], v[86:87], 0, s[0:1]
	global_load_dwordx4 v[6:9], v[86:87], off
	global_load_dwordx4 v[10:13], v[94:95], off
	global_load_dwordx4 v[14:17], v[96:97], off
	global_load_dwordx4 v[82:85], v[98:99], off
	global_load_dword v4, v[88:89], off
	global_load_dword v2, v[90:91], off
	global_load_dword v3, v[92:93], off
	s_waitcnt vmcnt(0)
	ds_write_b128 v227, v[6:9]
	ds_write_b128 v228, v[10:13]
	ds_write_b128 v229, v[14:17]
	ds_write_b128 v230, v[82:85]
	s_and_saveexec_b64 s[8:9], s[2:3]
	ds_write_b32 v132, v4
	s_or_b64 exec, exec, s[8:9]
	s_mov_b32 s18, s6
	ds_write2st64_b32 v133, v2, v3 offset1:4

.LBB0_771:
	s_add_i32 s14, s4, s94
	s_cmpk_lt_i32 s14, 0x4200
	s_cselect_b64 s[8:9], -1, 0
	s_and_b64 s[0:1], s[8:9], exec
	s_cselect_b32 s6, s14, s4
	s_ashr_i32 s7, s6, 31
	s_lshl_b64 s[0:1], s[6:7], 12
	v_lshl_add_u64 v[32:33], v[80:81], 0, s[0:1]
	s_waitcnt vmcnt(4)
	global_load_dwordx4 v[62:65], v[32:33], off
	global_load_dwordx4 v[58:61], v[32:33], off offset:1024
	global_load_dwordx4 v[54:57], v[32:33], off offset:2048
	global_load_dwordx4 v[50:53], v[32:33], off offset:3072
	v_cvt_f32_f16_sdwa v167, v46 dst_sel:DWORD dst_unused:UNUSED_PAD src0_sel:WORD_1
	v_cvt_f32_f16_e32 v166, v46
	v_cvt_f32_f16_sdwa v163, v47 dst_sel:DWORD dst_unused:UNUSED_PAD src0_sel:WORD_1
	v_cvt_f32_f16_e32 v162, v47
	v_cvt_f32_f16_sdwa v161, v48 dst_sel:DWORD dst_unused:UNUSED_PAD src0_sel:WORD_1
	v_cvt_f32_f16_e32 v160, v48
	v_cvt_f32_f16_sdwa v165, v49 dst_sel:DWORD dst_unused:UNUSED_PAD src0_sel:WORD_1
	v_cvt_f32_f16_e32 v164, v49
	v_cvt_f32_f16_sdwa v155, v42 dst_sel:DWORD dst_unused:UNUSED_PAD src0_sel:WORD_1
	v_cvt_f32_f16_e32 v154, v42
	v_cvt_f32_f16_sdwa v157, v43 dst_sel:DWORD dst_unused:UNUSED_PAD src0_sel:WORD_1
	v_cvt_f32_f16_e32 v156, v43
	v_cvt_f32_f16_sdwa v153, v44 dst_sel:DWORD dst_unused:UNUSED_PAD src0_sel:WORD_1
	v_cvt_f32_f16_e32 v152, v44
	v_cvt_f32_f16_sdwa v159, v45 dst_sel:DWORD dst_unused:UNUSED_PAD src0_sel:WORD_1
	v_cvt_f32_f16_e32 v158, v45
	v_cvt_f32_f16_sdwa v45, v38 dst_sel:DWORD dst_unused:UNUSED_PAD src0_sel:WORD_1
	v_cvt_f32_f16_e32 v44, v38
	v_cvt_f32_f16_sdwa v47, v39 dst_sel:DWORD dst_unused:UNUSED_PAD src0_sel:WORD_1
	v_cvt_f32_f16_e32 v46, v39
	v_cvt_f32_f16_sdwa v43, v40 dst_sel:DWORD dst_unused:UNUSED_PAD src0_sel:WORD_1
	v_cvt_f32_f16_e32 v42, v40
	v_cvt_f32_f16_sdwa v49, v41 dst_sel:DWORD dst_unused:UNUSED_PAD src0_sel:WORD_1
	v_cvt_f32_f16_e32 v48, v41
	v_cvt_f32_f16_sdwa v39, v34 dst_sel:DWORD dst_unused:UNUSED_PAD src0_sel:WORD_1
	v_cvt_f32_f16_e32 v38, v34
	v_cvt_f32_f16_sdwa v41, v35 dst_sel:DWORD dst_unused:UNUSED_PAD src0_sel:WORD_1
	v_cvt_f32_f16_e32 v40, v35
	v_cvt_f32_f16_sdwa v33, v36 dst_sel:DWORD dst_unused:UNUSED_PAD src0_sel:WORD_1
	v_cvt_f32_f16_e32 v32, v36
	v_cvt_f32_f16_sdwa v35, v37 dst_sel:DWORD dst_unused:UNUSED_PAD src0_sel:WORD_1
	v_cvt_f32_f16_e32 v34, v37
	s_cmpk_gt_i32 s4, 0x3fff
	s_cselect_b64 s[2:3], -1, 0
	s_cmpk_lt_i32 s4, 0x4000
	s_cbranch_scc1 .LBB0_773
	s_add_i32 s86, s4, 0xffffc000
	s_lshl_b64 s[0:1], s[86:87], 13
	v_lshl_add_u64 v[36:37], v[82:83], 0, s[0:1]
	global_load_dwordx4 v[190:193], v[36:37], off nt
	global_load_dwordx4 v[194:197], v[36:37], off offset:16 nt
	global_load_dwordx4 v[198:201], v[36:37], off offset:2048 nt
	global_load_dwordx4 v[204:207], v[36:37], off offset:2064 nt
	s_mov_b64 s[0:1], 0x400000
	v_lshl_add_u64 v[232:233], v[36:37], 0, s[0:1]
	global_load_dwordx4 v[208:211], v[232:233], off nt
	global_load_dwordx4 v[212:215], v[232:233], off offset:16 nt
	global_load_dwordx4 v[216:219], v[232:233], off offset:2048 nt
	global_load_dwordx4 v[220:223], v[232:233], off offset:2064 nt
	s_mov_b64 s[0:1], 0x800000
	v_lshl_add_u64 v[232:233], v[36:37], 0, s[0:1]
	global_load_dwordx4 v[224:227], v[232:233], off nt
	global_load_dwordx4 v[228:231], v[232:233], off offset:16 nt
	global_load_dwordx4 v[238:241], v[232:233], off offset:2048 nt
	global_load_dwordx4 v[242:245], v[232:233], off offset:2064 nt
	s_waitcnt vmcnt(8)
	v_mov_b64_e32 v[174:175], v[190:191]
	v_mov_b64_e32 v[176:177], v[192:193]
	v_mov_b64_e32 v[178:179], v[194:195]
	v_mov_b64_e32 v[180:181], v[196:197]
	v_mov_b64_e32 v[182:183], v[198:199]
	v_mov_b64_e32 v[184:185], v[200:201]
	v_mov_b64_e32 v[186:187], v[204:205]
	v_mov_b64_e32 v[188:189], v[206:207]
	s_mov_b64 s[0:1], 0xc00000
	v_lshl_add_u64 v[232:233], v[36:37], 0, s[0:1]
	global_load_dwordx4 v[190:193], v[232:233], off nt
	global_load_dwordx4 v[194:197], v[232:233], off offset:16 nt
	global_load_dwordx4 v[198:201], v[232:233], off offset:2048 nt
	global_load_dwordx4 v[204:207], v[232:233], off offset:2064 nt
	s_waitcnt vmcnt(8)
	v_pk_add_f32 v[174:175], v[174:175], v[208:209]
	v_pk_add_f32 v[176:177], v[176:177], v[210:211]
	v_pk_add_f32 v[178:179], v[178:179], v[212:213]
	v_pk_add_f32 v[180:181], v[180:181], v[214:215]
	v_pk_add_f32 v[182:183], v[182:183], v[216:217]
	v_pk_add_f32 v[184:185], v[184:185], v[218:219]
	v_pk_add_f32 v[186:187], v[186:187], v[220:221]
	v_pk_add_f32 v[188:189], v[188:189], v[222:223]
	s_mov_b64 s[0:1], 0x1000000
	v_lshl_add_u64 v[232:233], v[36:37], 0, s[0:1]
	global_load_dwordx4 v[208:211], v[232:233], off nt
	global_load_dwordx4 v[212:215], v[232:233], off offset:16 nt
	global_load_dwordx4 v[216:219], v[232:233], off offset:2048 nt
	global_load_dwordx4 v[220:223], v[232:233], off offset:2064 nt
	s_waitcnt vmcnt(8)
	v_pk_add_f32 v[174:175], v[174:175], v[224:225]
	v_pk_add_f32 v[176:177], v[176:177], v[226:227]
	v_pk_add_f32 v[178:179], v[178:179], v[228:229]
	v_pk_add_f32 v[180:181], v[180:181], v[230:231]
	v_pk_add_f32 v[182:183], v[182:183], v[238:239]
	v_pk_add_f32 v[184:185], v[184:185], v[240:241]
	v_pk_add_f32 v[186:187], v[186:187], v[242:243]
	v_pk_add_f32 v[188:189], v[188:189], v[244:245]
	s_mov_b64 s[0:1], 0x1400000
	v_lshl_add_u64 v[232:233], v[36:37], 0, s[0:1]
	global_load_dwordx4 v[224:227], v[232:233], off nt
	global_load_dwordx4 v[228:231], v[232:233], off offset:16 nt
	global_load_dwordx4 v[238:241], v[232:233], off offset:2048 nt
	global_load_dwordx4 v[242:245], v[232:233], off offset:2064 nt
	s_waitcnt vmcnt(8)
	v_pk_add_f32 v[174:175], v[174:175], v[190:191]
	v_pk_add_f32 v[176:177], v[176:177], v[192:193]
	v_pk_add_f32 v[178:179], v[178:179], v[194:195]
	v_pk_add_f32 v[180:181], v[180:181], v[196:197]
	v_pk_add_f32 v[182:183], v[182:183], v[198:199]
	v_pk_add_f32 v[184:185], v[184:185], v[200:201]
	v_pk_add_f32 v[186:187], v[186:187], v[204:205]
	v_pk_add_f32 v[188:189], v[188:189], v[206:207]
	s_mov_b64 s[0:1], 0x1800000
	v_lshl_add_u64 v[232:233], v[36:37], 0, s[0:1]
	global_load_dwordx4 v[190:193], v[232:233], off nt
	global_load_dwordx4 v[194:197], v[232:233], off offset:16 nt
	global_load_dwordx4 v[198:201], v[232:233], off offset:2048 nt
	global_load_dwordx4 v[204:207], v[232:233], off offset:2064 nt
	s_waitcnt vmcnt(8)
	v_pk_add_f32 v[174:175], v[174:175], v[208:209]
	v_pk_add_f32 v[176:177], v[176:177], v[210:211]
	v_pk_add_f32 v[178:179], v[178:179], v[212:213]
	v_pk_add_f32 v[180:181], v[180:181], v[214:215]
	v_pk_add_f32 v[182:183], v[182:183], v[216:217]
	v_pk_add_f32 v[184:185], v[184:185], v[218:219]
	v_pk_add_f32 v[186:187], v[186:187], v[220:221]
	v_pk_add_f32 v[188:189], v[188:189], v[222:223]
	s_mov_b64 s[0:1], 0x1c00000
	v_lshl_add_u64 v[232:233], v[36:37], 0, s[0:1]
	global_load_dwordx4 v[208:211], v[232:233], off nt
	global_load_dwordx4 v[212:215], v[232:233], off offset:16 nt
	global_load_dwordx4 v[216:219], v[232:233], off offset:2048 nt
	global_load_dwordx4 v[220:223], v[232:233], off offset:2064 nt
	s_waitcnt vmcnt(8)
	v_pk_add_f32 v[174:175], v[174:175], v[224:225]
	v_pk_add_f32 v[176:177], v[176:177], v[226:227]
	v_pk_add_f32 v[178:179], v[178:179], v[228:229]
	v_pk_add_f32 v[180:181], v[180:181], v[230:231]
	v_pk_add_f32 v[182:183], v[182:183], v[238:239]
	v_pk_add_f32 v[184:185], v[184:185], v[240:241]
	v_pk_add_f32 v[186:187], v[186:187], v[242:243]
	v_pk_add_f32 v[188:189], v[188:189], v[244:245]
	global_load_dwordx4 v[224:227], v[74:75], off
	global_load_dwordx4 v[228:231], v[74:75], off offset:16
	global_load_dwordx4 v[238:241], v[74:75], off offset:2048
	global_load_dwordx4 v[242:245], v[74:75], off offset:2064
	s_waitcnt vmcnt(8)
	v_pk_add_f32 v[174:175], v[174:175], v[190:191]
	v_pk_add_f32 v[176:177], v[176:177], v[192:193]
	v_pk_add_f32 v[178:179], v[178:179], v[194:195]
	v_pk_add_f32 v[180:181], v[180:181], v[196:197]
	v_pk_add_f32 v[182:183], v[182:183], v[198:199]
	v_pk_add_f32 v[184:185], v[184:185], v[200:201]
	v_pk_add_f32 v[186:187], v[186:187], v[204:205]
	v_pk_add_f32 v[188:189], v[188:189], v[206:207]
	s_mov_b64 s[0:1], 0x1000
	v_lshl_add_u64 v[232:233], v[36:37], 0, s[0:1]
	global_load_dwordx4 v[190:193], v[232:233], off nt
	global_load_dwordx4 v[194:197], v[232:233], off offset:16 nt
	global_load_dwordx4 v[198:201], v[232:233], off offset:2048 nt
	global_load_dwordx4 v[204:207], v[232:233], off offset:2064 nt
	s_waitcnt vmcnt(8)
	v_pk_add_f32 v[174:175], v[174:175], v[208:209]
	v_pk_add_f32 v[176:177], v[176:177], v[210:211]
	v_pk_add_f32 v[178:179], v[178:179], v[212:213]
	v_pk_add_f32 v[180:181], v[180:181], v[214:215]
	v_pk_add_f32 v[182:183], v[182:183], v[216:217]
	v_pk_add_f32 v[184:185], v[184:185], v[218:219]
	v_pk_add_f32 v[186:187], v[186:187], v[220:221]
	v_pk_add_f32 v[188:189], v[188:189], v[222:223]
	s_mov_b64 s[0:1], 0x401000
	v_lshl_add_u64 v[232:233], v[36:37], 0, s[0:1]
	global_load_dwordx4 v[208:211], v[232:233], off nt
	global_load_dwordx4 v[212:215], v[232:233], off offset:16 nt
	global_load_dwordx4 v[216:219], v[232:233], off offset:2048 nt
	global_load_dwordx4 v[220:223], v[232:233], off offset:2064 nt
	s_waitcnt vmcnt(8)
	v_pk_fma_f32 v[166:167], v[174:175], v[224:225], v[166:167]
	v_pk_fma_f32 v[162:163], v[176:177], v[226:227], v[162:163]
	v_pk_fma_f32 v[160:161], v[178:179], v[228:229], v[160:161]
	v_pk_fma_f32 v[164:165], v[180:181], v[230:231], v[164:165]
	v_pk_fma_f32 v[154:155], v[182:183], v[238:239], v[154:155]
	v_pk_fma_f32 v[156:157], v[184:185], v[240:241], v[156:157]
	v_pk_fma_f32 v[152:153], v[186:187], v[242:243], v[152:153]
	v_pk_fma_f32 v[158:159], v[188:189], v[244:245], v[158:159]
	s_mov_b64 s[0:1], 0x801000
	v_lshl_add_u64 v[232:233], v[36:37], 0, s[0:1]
	global_load_dwordx4 v[224:227], v[232:233], off nt
	global_load_dwordx4 v[228:231], v[232:233], off offset:16 nt
	global_load_dwordx4 v[238:241], v[232:233], off offset:2048 nt
	global_load_dwordx4 v[242:245], v[232:233], off offset:2064 nt
	s_waitcnt vmcnt(8)
	v_mov_b64_e32 v[174:175], v[190:191]
	v_mov_b64_e32 v[176:177], v[192:193]
	v_mov_b64_e32 v[178:179], v[194:195]
	v_mov_b64_e32 v[180:181], v[196:197]
	v_mov_b64_e32 v[182:183], v[198:199]
	v_mov_b64_e32 v[184:185], v[200:201]
	v_mov_b64_e32 v[186:187], v[204:205]
	v_mov_b64_e32 v[188:189], v[206:207]
	s_mov_b64 s[0:1], 0xc01000
	v_lshl_add_u64 v[232:233], v[36:37], 0, s[0:1]
	global_load_dwordx4 v[190:193], v[232:233], off nt
	global_load_dwordx4 v[194:197], v[232:233], off offset:16 nt
	global_load_dwordx4 v[198:201], v[232:233], off offset:2048 nt
	global_load_dwordx4 v[204:207], v[232:233], off offset:2064 nt
	s_waitcnt vmcnt(8)
	v_pk_add_f32 v[174:175], v[174:175], v[208:209]
	v_pk_add_f32 v[176:177], v[176:177], v[210:211]
	v_pk_add_f32 v[178:179], v[178:179], v[212:213]
	v_pk_add_f32 v[180:181], v[180:181], v[214:215]
	v_pk_add_f32 v[182:183], v[182:183], v[216:217]
	v_pk_add_f32 v[184:185], v[184:185], v[218:219]
	v_pk_add_f32 v[186:187], v[186:187], v[220:221]
	v_pk_add_f32 v[188:189], v[188:189], v[222:223]
	s_mov_b64 s[0:1], 0x1001000
	v_lshl_add_u64 v[232:233], v[36:37], 0, s[0:1]
	global_load_dwordx4 v[208:211], v[232:233], off nt
	global_load_dwordx4 v[212:215], v[232:233], off offset:16 nt
	global_load_dwordx4 v[216:219], v[232:233], off offset:2048 nt
	global_load_dwordx4 v[220:223], v[232:233], off offset:2064 nt
	s_waitcnt vmcnt(8)
	v_pk_add_f32 v[174:175], v[174:175], v[224:225]
	v_pk_add_f32 v[176:177], v[176:177], v[226:227]
	v_pk_add_f32 v[178:179], v[178:179], v[228:229]
	v_pk_add_f32 v[180:181], v[180:181], v[230:231]
	v_pk_add_f32 v[182:183], v[182:183], v[238:239]
	v_pk_add_f32 v[184:185], v[184:185], v[240:241]
	v_pk_add_f32 v[186:187], v[186:187], v[242:243]
	v_pk_add_f32 v[188:189], v[188:189], v[244:245]
	s_mov_b64 s[0:1], 0x1401000
	v_lshl_add_u64 v[232:233], v[36:37], 0, s[0:1]
	global_load_dwordx4 v[224:227], v[232:233], off nt
	global_load_dwordx4 v[228:231], v[232:233], off offset:16 nt
	global_load_dwordx4 v[238:241], v[232:233], off offset:2048 nt
	global_load_dwordx4 v[242:245], v[232:233], off offset:2064 nt
	s_waitcnt vmcnt(8)
	v_pk_add_f32 v[174:175], v[174:175], v[190:191]
	v_pk_add_f32 v[176:177], v[176:177], v[192:193]
	v_pk_add_f32 v[178:179], v[178:179], v[194:195]
	v_pk_add_f32 v[180:181], v[180:181], v[196:197]
	v_pk_add_f32 v[182:183], v[182:183], v[198:199]
	v_pk_add_f32 v[184:185], v[184:185], v[200:201]
	v_pk_add_f32 v[186:187], v[186:187], v[204:205]
	v_pk_add_f32 v[188:189], v[188:189], v[206:207]
	s_mov_b64 s[0:1], 0x1801000
	v_lshl_add_u64 v[232:233], v[36:37], 0, s[0:1]
	global_load_dwordx4 v[190:193], v[232:233], off nt
	global_load_dwordx4 v[194:197], v[232:233], off offset:16 nt
	global_load_dwordx4 v[198:201], v[232:233], off offset:2048 nt
	global_load_dwordx4 v[204:207], v[232:233], off offset:2064 nt
	s_waitcnt vmcnt(8)
	v_pk_add_f32 v[174:175], v[174:175], v[208:209]
	v_pk_add_f32 v[176:177], v[176:177], v[210:211]
	v_pk_add_f32 v[178:179], v[178:179], v[212:213]
	v_pk_add_f32 v[180:181], v[180:181], v[214:215]
	v_pk_add_f32 v[182:183], v[182:183], v[216:217]
	v_pk_add_f32 v[184:185], v[184:185], v[218:219]
	v_pk_add_f32 v[186:187], v[186:187], v[220:221]
	v_pk_add_f32 v[188:189], v[188:189], v[222:223]
	s_mov_b64 s[0:1], 0x1c01000
	v_lshl_add_u64 v[232:233], v[36:37], 0, s[0:1]
	global_load_dwordx4 v[208:211], v[232:233], off nt
	global_load_dwordx4 v[212:215], v[232:233], off offset:16 nt
	global_load_dwordx4 v[216:219], v[232:233], off offset:2048 nt
	global_load_dwordx4 v[220:223], v[232:233], off offset:2064 nt
	s_waitcnt vmcnt(8)
	v_pk_add_f32 v[174:175], v[174:175], v[224:225]
	v_pk_add_f32 v[176:177], v[176:177], v[226:227]
	v_pk_add_f32 v[178:179], v[178:179], v[228:229]
	v_pk_add_f32 v[180:181], v[180:181], v[230:231]
	v_pk_add_f32 v[182:183], v[182:183], v[238:239]
	v_pk_add_f32 v[184:185], v[184:185], v[240:241]
	v_pk_add_f32 v[186:187], v[186:187], v[242:243]
	v_pk_add_f32 v[188:189], v[188:189], v[244:245]
	global_load_dwordx4 v[224:227], v[76:77], off
	global_load_dwordx4 v[228:231], v[76:77], off offset:16
	global_load_dwordx4 v[238:241], v[78:79], off
	global_load_dwordx4 v[242:245], v[78:79], off offset:16
	s_waitcnt vmcnt(8)
	v_pk_add_f32 v[174:175], v[174:175], v[190:191]
	v_pk_add_f32 v[176:177], v[176:177], v[192:193]
	v_pk_add_f32 v[178:179], v[178:179], v[194:195]
	v_pk_add_f32 v[180:181], v[180:181], v[196:197]
	v_pk_add_f32 v[182:183], v[182:183], v[198:199]
	v_pk_add_f32 v[184:185], v[184:185], v[200:201]
	v_pk_add_f32 v[186:187], v[186:187], v[204:205]
	v_pk_add_f32 v[188:189], v[188:189], v[206:207]
	s_waitcnt vmcnt(4)
	v_pk_add_f32 v[174:175], v[174:175], v[208:209]
	v_pk_add_f32 v[176:177], v[176:177], v[210:211]
	v_pk_add_f32 v[178:179], v[178:179], v[212:213]
	v_pk_add_f32 v[180:181], v[180:181], v[214:215]
	v_pk_add_f32 v[182:183], v[182:183], v[216:217]
	v_pk_add_f32 v[184:185], v[184:185], v[218:219]
	v_pk_add_f32 v[186:187], v[186:187], v[220:221]
	v_pk_add_f32 v[188:189], v[188:189], v[222:223]
	s_waitcnt vmcnt(0)
	v_pk_fma_f32 v[44:45], v[174:175], v[224:225], v[44:45]
	v_pk_fma_f32 v[46:47], v[176:177], v[226:227], v[46:47]
	v_pk_fma_f32 v[42:43], v[178:179], v[228:229], v[42:43]
	v_pk_fma_f32 v[48:49], v[180:181], v[230:231], v[48:49]
	v_pk_fma_f32 v[38:39], v[182:183], v[238:239], v[38:39]
	v_pk_fma_f32 v[40:41], v[184:185], v[240:241], v[40:41]
	v_pk_fma_f32 v[32:33], v[186:187], v[242:243], v[32:33]
	v_pk_fma_f32 v[34:35], v[188:189], v[244:245], v[34:35]

.LBB0_777:
	s_add_i32 s0, s75, s4
	s_cmpk_lt_i32 s0, 0x4200
	s_cselect_b32 s0, s0, s4
	s_ashr_i32 s1, s0, 31
	s_lshl_b64 s[0:1], s[0:1], 12
	v_lshl_add_u64 v[32:33], v[80:81], 0, s[0:1]
	global_load_dwordx4 v[46:49], v[32:33], off
	global_load_dwordx4 v[42:45], v[32:33], off offset:1024
	global_load_dwordx4 v[38:41], v[32:33], off offset:2048
	global_load_dwordx4 v[34:37], v[32:33], off offset:3072
	s_waitcnt vmcnt(8)
	s_andn2_b64 vcc, exec, s[8:9]
	s_cbranch_vccnz .LBB0_767
	v_cvt_f32_f16_sdwa v167, v62 dst_sel:DWORD dst_unused:UNUSED_PAD src0_sel:WORD_1
	v_cvt_f32_f16_e32 v166, v62
	v_cvt_f32_f16_sdwa v163, v63 dst_sel:DWORD dst_unused:UNUSED_PAD src0_sel:WORD_1
	v_cvt_f32_f16_e32 v162, v63
	v_cvt_f32_f16_sdwa v161, v64 dst_sel:DWORD dst_unused:UNUSED_PAD src0_sel:WORD_1
	v_cvt_f32_f16_e32 v160, v64
	v_cvt_f32_f16_sdwa v165, v65 dst_sel:DWORD dst_unused:UNUSED_PAD src0_sel:WORD_1
	v_cvt_f32_f16_e32 v164, v65
	v_cvt_f32_f16_sdwa v155, v58 dst_sel:DWORD dst_unused:UNUSED_PAD src0_sel:WORD_1
	v_cvt_f32_f16_e32 v154, v58
	v_cvt_f32_f16_sdwa v157, v59 dst_sel:DWORD dst_unused:UNUSED_PAD src0_sel:WORD_1
	v_cvt_f32_f16_e32 v156, v59
	v_cvt_f32_f16_sdwa v153, v60 dst_sel:DWORD dst_unused:UNUSED_PAD src0_sel:WORD_1
	v_cvt_f32_f16_e32 v152, v60
	v_cvt_f32_f16_sdwa v159, v61 dst_sel:DWORD dst_unused:UNUSED_PAD src0_sel:WORD_1
	v_cvt_f32_f16_e32 v158, v61
	v_cvt_f32_f16_sdwa v61, v54 dst_sel:DWORD dst_unused:UNUSED_PAD src0_sel:WORD_1
	v_cvt_f32_f16_e32 v60, v54
	v_cvt_f32_f16_sdwa v63, v55 dst_sel:DWORD dst_unused:UNUSED_PAD src0_sel:WORD_1
	v_cvt_f32_f16_e32 v62, v55
	v_cvt_f32_f16_sdwa v59, v56 dst_sel:DWORD dst_unused:UNUSED_PAD src0_sel:WORD_1
	v_cvt_f32_f16_e32 v58, v56
	v_cvt_f32_f16_sdwa v65, v57 dst_sel:DWORD dst_unused:UNUSED_PAD src0_sel:WORD_1
	v_cvt_f32_f16_e32 v64, v57
	v_cvt_f32_f16_sdwa v55, v50 dst_sel:DWORD dst_unused:UNUSED_PAD src0_sel:WORD_1
	v_cvt_f32_f16_e32 v54, v50
	v_cvt_f32_f16_sdwa v57, v51 dst_sel:DWORD dst_unused:UNUSED_PAD src0_sel:WORD_1
	v_cvt_f32_f16_e32 v56, v51
	v_cvt_f32_f16_sdwa v33, v52 dst_sel:DWORD dst_unused:UNUSED_PAD src0_sel:WORD_1
	v_cvt_f32_f16_e32 v32, v52
	v_cvt_f32_f16_sdwa v51, v53 dst_sel:DWORD dst_unused:UNUSED_PAD src0_sel:WORD_1
	v_cvt_f32_f16_e32 v50, v53
	s_cmpk_gt_i32 s14, 0x3fff
	s_cselect_b64 s[2:3], -1, 0
	s_cmpk_lt_i32 s14, 0x4000
	s_cbranch_scc1 .LBB0_780
	s_add_i32 s86, s14, 0xffffc000
	s_lshl_b64 s[0:1], s[86:87], 13
	v_lshl_add_u64 v[52:53], v[82:83], 0, s[0:1]
	global_load_dwordx4 v[190:193], v[52:53], off nt
	global_load_dwordx4 v[194:197], v[52:53], off offset:16 nt
	global_load_dwordx4 v[198:201], v[52:53], off offset:2048 nt
	global_load_dwordx4 v[204:207], v[52:53], off offset:2064 nt
	s_mov_b64 s[0:1], 0x400000
	v_lshl_add_u64 v[232:233], v[52:53], 0, s[0:1]
	global_load_dwordx4 v[208:211], v[232:233], off nt
	global_load_dwordx4 v[212:215], v[232:233], off offset:16 nt
	global_load_dwordx4 v[216:219], v[232:233], off offset:2048 nt
	global_load_dwordx4 v[220:223], v[232:233], off offset:2064 nt
	s_mov_b64 s[0:1], 0x800000
	v_lshl_add_u64 v[232:233], v[52:53], 0, s[0:1]
	global_load_dwordx4 v[224:227], v[232:233], off nt
	global_load_dwordx4 v[228:231], v[232:233], off offset:16 nt
	global_load_dwordx4 v[238:241], v[232:233], off offset:2048 nt
	global_load_dwordx4 v[242:245], v[232:233], off offset:2064 nt
	s_waitcnt vmcnt(8)
	v_mov_b64_e32 v[174:175], v[190:191]
	v_mov_b64_e32 v[176:177], v[192:193]
	v_mov_b64_e32 v[178:179], v[194:195]
	v_mov_b64_e32 v[180:181], v[196:197]
	v_mov_b64_e32 v[182:183], v[198:199]
	v_mov_b64_e32 v[184:185], v[200:201]
	v_mov_b64_e32 v[186:187], v[204:205]
	v_mov_b64_e32 v[188:189], v[206:207]
	s_mov_b64 s[0:1], 0xc00000
	v_lshl_add_u64 v[232:233], v[52:53], 0, s[0:1]
	global_load_dwordx4 v[190:193], v[232:233], off nt
	global_load_dwordx4 v[194:197], v[232:233], off offset:16 nt
	global_load_dwordx4 v[198:201], v[232:233], off offset:2048 nt
	global_load_dwordx4 v[204:207], v[232:233], off offset:2064 nt
	s_waitcnt vmcnt(8)
	v_pk_add_f32 v[174:175], v[174:175], v[208:209]
	v_pk_add_f32 v[176:177], v[176:177], v[210:211]
	v_pk_add_f32 v[178:179], v[178:179], v[212:213]
	v_pk_add_f32 v[180:181], v[180:181], v[214:215]
	v_pk_add_f32 v[182:183], v[182:183], v[216:217]
	v_pk_add_f32 v[184:185], v[184:185], v[218:219]
	v_pk_add_f32 v[186:187], v[186:187], v[220:221]
	v_pk_add_f32 v[188:189], v[188:189], v[222:223]
	s_mov_b64 s[0:1], 0x1000000
	v_lshl_add_u64 v[232:233], v[52:53], 0, s[0:1]
	global_load_dwordx4 v[208:211], v[232:233], off nt
	global_load_dwordx4 v[212:215], v[232:233], off offset:16 nt
	global_load_dwordx4 v[216:219], v[232:233], off offset:2048 nt
	global_load_dwordx4 v[220:223], v[232:233], off offset:2064 nt
	s_waitcnt vmcnt(8)
	v_pk_add_f32 v[174:175], v[174:175], v[224:225]
	v_pk_add_f32 v[176:177], v[176:177], v[226:227]
	v_pk_add_f32 v[178:179], v[178:179], v[228:229]
	v_pk_add_f32 v[180:181], v[180:181], v[230:231]
	v_pk_add_f32 v[182:183], v[182:183], v[238:239]
	v_pk_add_f32 v[184:185], v[184:185], v[240:241]
	v_pk_add_f32 v[186:187], v[186:187], v[242:243]
	v_pk_add_f32 v[188:189], v[188:189], v[244:245]
	s_mov_b64 s[0:1], 0x1400000
	v_lshl_add_u64 v[232:233], v[52:53], 0, s[0:1]
	global_load_dwordx4 v[224:227], v[232:233], off nt
	global_load_dwordx4 v[228:231], v[232:233], off offset:16 nt
	global_load_dwordx4 v[238:241], v[232:233], off offset:2048 nt
	global_load_dwordx4 v[242:245], v[232:233], off offset:2064 nt
	s_waitcnt vmcnt(8)
	v_pk_add_f32 v[174:175], v[174:175], v[190:191]
	v_pk_add_f32 v[176:177], v[176:177], v[192:193]
	v_pk_add_f32 v[178:179], v[178:179], v[194:195]
	v_pk_add_f32 v[180:181], v[180:181], v[196:197]
	v_pk_add_f32 v[182:183], v[182:183], v[198:199]
	v_pk_add_f32 v[184:185], v[184:185], v[200:201]
	v_pk_add_f32 v[186:187], v[186:187], v[204:205]
	v_pk_add_f32 v[188:189], v[188:189], v[206:207]
	s_mov_b64 s[0:1], 0x1800000
	v_lshl_add_u64 v[232:233], v[52:53], 0, s[0:1]
	global_load_dwordx4 v[190:193], v[232:233], off nt
	global_load_dwordx4 v[194:197], v[232:233], off offset:16 nt
	global_load_dwordx4 v[198:201], v[232:233], off offset:2048 nt
	global_load_dwordx4 v[204:207], v[232:233], off offset:2064 nt
	s_waitcnt vmcnt(8)
	v_pk_add_f32 v[174:175], v[174:175], v[208:209]
	v_pk_add_f32 v[176:177], v[176:177], v[210:211]
	v_pk_add_f32 v[178:179], v[178:179], v[212:213]
	v_pk_add_f32 v[180:181], v[180:181], v[214:215]
	v_pk_add_f32 v[182:183], v[182:183], v[216:217]
	v_pk_add_f32 v[184:185], v[184:185], v[218:219]
	v_pk_add_f32 v[186:187], v[186:187], v[220:221]
	v_pk_add_f32 v[188:189], v[188:189], v[222:223]
	s_mov_b64 s[0:1], 0x1c00000
	v_lshl_add_u64 v[232:233], v[52:53], 0, s[0:1]
	global_load_dwordx4 v[208:211], v[232:233], off nt
	global_load_dwordx4 v[212:215], v[232:233], off offset:16 nt
	global_load_dwordx4 v[216:219], v[232:233], off offset:2048 nt
	global_load_dwordx4 v[220:223], v[232:233], off offset:2064 nt
	s_waitcnt vmcnt(8)
	v_pk_add_f32 v[174:175], v[174:175], v[224:225]
	v_pk_add_f32 v[176:177], v[176:177], v[226:227]
	v_pk_add_f32 v[178:179], v[178:179], v[228:229]
	v_pk_add_f32 v[180:181], v[180:181], v[230:231]
	v_pk_add_f32 v[182:183], v[182:183], v[238:239]
	v_pk_add_f32 v[184:185], v[184:185], v[240:241]
	v_pk_add_f32 v[186:187], v[186:187], v[242:243]
	v_pk_add_f32 v[188:189], v[188:189], v[244:245]
	global_load_dwordx4 v[224:227], v[74:75], off
	global_load_dwordx4 v[228:231], v[74:75], off offset:16
	global_load_dwordx4 v[238:241], v[74:75], off offset:2048
	global_load_dwordx4 v[242:245], v[74:75], off offset:2064
	s_waitcnt vmcnt(8)
	v_pk_add_f32 v[174:175], v[174:175], v[190:191]
	v_pk_add_f32 v[176:177], v[176:177], v[192:193]
	v_pk_add_f32 v[178:179], v[178:179], v[194:195]
	v_pk_add_f32 v[180:181], v[180:181], v[196:197]
	v_pk_add_f32 v[182:183], v[182:183], v[198:199]
	v_pk_add_f32 v[184:185], v[184:185], v[200:201]
	v_pk_add_f32 v[186:187], v[186:187], v[204:205]
	v_pk_add_f32 v[188:189], v[188:189], v[206:207]
	s_mov_b64 s[0:1], 0x1000
	v_lshl_add_u64 v[232:233], v[52:53], 0, s[0:1]
	global_load_dwordx4 v[190:193], v[232:233], off nt
	global_load_dwordx4 v[194:197], v[232:233], off offset:16 nt
	global_load_dwordx4 v[198:201], v[232:233], off offset:2048 nt
	global_load_dwordx4 v[204:207], v[232:233], off offset:2064 nt
	s_waitcnt vmcnt(8)
	v_pk_add_f32 v[174:175], v[174:175], v[208:209]
	v_pk_add_f32 v[176:177], v[176:177], v[210:211]
	v_pk_add_f32 v[178:179], v[178:179], v[212:213]
	v_pk_add_f32 v[180:181], v[180:181], v[214:215]
	v_pk_add_f32 v[182:183], v[182:183], v[216:217]
	v_pk_add_f32 v[184:185], v[184:185], v[218:219]
	v_pk_add_f32 v[186:187], v[186:187], v[220:221]
	v_pk_add_f32 v[188:189], v[188:189], v[222:223]
	s_mov_b64 s[0:1], 0x401000
	v_lshl_add_u64 v[232:233], v[52:53], 0, s[0:1]
	global_load_dwordx4 v[208:211], v[232:233], off nt
	global_load_dwordx4 v[212:215], v[232:233], off offset:16 nt
	global_load_dwordx4 v[216:219], v[232:233], off offset:2048 nt
	global_load_dwordx4 v[220:223], v[232:233], off offset:2064 nt
	s_waitcnt vmcnt(8)
	v_pk_fma_f32 v[166:167], v[174:175], v[224:225], v[166:167]
	v_pk_fma_f32 v[162:163], v[176:177], v[226:227], v[162:163]
	v_pk_fma_f32 v[160:161], v[178:179], v[228:229], v[160:161]
	v_pk_fma_f32 v[164:165], v[180:181], v[230:231], v[164:165]
	v_pk_fma_f32 v[154:155], v[182:183], v[238:239], v[154:155]
	v_pk_fma_f32 v[156:157], v[184:185], v[240:241], v[156:157]
	v_pk_fma_f32 v[152:153], v[186:187], v[242:243], v[152:153]
	v_pk_fma_f32 v[158:159], v[188:189], v[244:245], v[158:159]
	s_mov_b64 s[0:1], 0x801000
	v_lshl_add_u64 v[232:233], v[52:53], 0, s[0:1]
	global_load_dwordx4 v[224:227], v[232:233], off nt
	global_load_dwordx4 v[228:231], v[232:233], off offset:16 nt
	global_load_dwordx4 v[238:241], v[232:233], off offset:2048 nt
	global_load_dwordx4 v[242:245], v[232:233], off offset:2064 nt
	s_waitcnt vmcnt(8)
	v_mov_b64_e32 v[174:175], v[190:191]
	v_mov_b64_e32 v[176:177], v[192:193]
	v_mov_b64_e32 v[178:179], v[194:195]
	v_mov_b64_e32 v[180:181], v[196:197]
	v_mov_b64_e32 v[182:183], v[198:199]
	v_mov_b64_e32 v[184:185], v[200:201]
	v_mov_b64_e32 v[186:187], v[204:205]
	v_mov_b64_e32 v[188:189], v[206:207]
	s_mov_b64 s[0:1], 0xc01000
	v_lshl_add_u64 v[232:233], v[52:53], 0, s[0:1]
	global_load_dwordx4 v[190:193], v[232:233], off nt
	global_load_dwordx4 v[194:197], v[232:233], off offset:16 nt
	global_load_dwordx4 v[198:201], v[232:233], off offset:2048 nt
	global_load_dwordx4 v[204:207], v[232:233], off offset:2064 nt
	s_waitcnt vmcnt(8)
	v_pk_add_f32 v[174:175], v[174:175], v[208:209]
	v_pk_add_f32 v[176:177], v[176:177], v[210:211]
	v_pk_add_f32 v[178:179], v[178:179], v[212:213]
	v_pk_add_f32 v[180:181], v[180:181], v[214:215]
	v_pk_add_f32 v[182:183], v[182:183], v[216:217]
	v_pk_add_f32 v[184:185], v[184:185], v[218:219]
	v_pk_add_f32 v[186:187], v[186:187], v[220:221]
	v_pk_add_f32 v[188:189], v[188:189], v[222:223]
	s_mov_b64 s[0:1], 0x1001000
	v_lshl_add_u64 v[232:233], v[52:53], 0, s[0:1]
	global_load_dwordx4 v[208:211], v[232:233], off nt
	global_load_dwordx4 v[212:215], v[232:233], off offset:16 nt
	global_load_dwordx4 v[216:219], v[232:233], off offset:2048 nt
	global_load_dwordx4 v[220:223], v[232:233], off offset:2064 nt
	s_waitcnt vmcnt(8)
	v_pk_add_f32 v[174:175], v[174:175], v[224:225]
	v_pk_add_f32 v[176:177], v[176:177], v[226:227]
	v_pk_add_f32 v[178:179], v[178:179], v[228:229]
	v_pk_add_f32 v[180:181], v[180:181], v[230:231]
	v_pk_add_f32 v[182:183], v[182:183], v[238:239]
	v_pk_add_f32 v[184:185], v[184:185], v[240:241]
	v_pk_add_f32 v[186:187], v[186:187], v[242:243]
	v_pk_add_f32 v[188:189], v[188:189], v[244:245]
	s_mov_b64 s[0:1], 0x1401000
	v_lshl_add_u64 v[232:233], v[52:53], 0, s[0:1]
	global_load_dwordx4 v[224:227], v[232:233], off nt
	global_load_dwordx4 v[228:231], v[232:233], off offset:16 nt
	global_load_dwordx4 v[238:241], v[232:233], off offset:2048 nt
	global_load_dwordx4 v[242:245], v[232:233], off offset:2064 nt
	s_waitcnt vmcnt(8)
	v_pk_add_f32 v[174:175], v[174:175], v[190:191]
	v_pk_add_f32 v[176:177], v[176:177], v[192:193]
	v_pk_add_f32 v[178:179], v[178:179], v[194:195]
	v_pk_add_f32 v[180:181], v[180:181], v[196:197]
	v_pk_add_f32 v[182:183], v[182:183], v[198:199]
	v_pk_add_f32 v[184:185], v[184:185], v[200:201]
	v_pk_add_f32 v[186:187], v[186:187], v[204:205]
	v_pk_add_f32 v[188:189], v[188:189], v[206:207]
	s_mov_b64 s[0:1], 0x1801000
	v_lshl_add_u64 v[232:233], v[52:53], 0, s[0:1]
	global_load_dwordx4 v[190:193], v[232:233], off nt
	global_load_dwordx4 v[194:197], v[232:233], off offset:16 nt
	global_load_dwordx4 v[198:201], v[232:233], off offset:2048 nt
	global_load_dwordx4 v[204:207], v[232:233], off offset:2064 nt
	s_waitcnt vmcnt(8)
	v_pk_add_f32 v[174:175], v[174:175], v[208:209]
	v_pk_add_f32 v[176:177], v[176:177], v[210:211]
	v_pk_add_f32 v[178:179], v[178:179], v[212:213]
	v_pk_add_f32 v[180:181], v[180:181], v[214:215]
	v_pk_add_f32 v[182:183], v[182:183], v[216:217]
	v_pk_add_f32 v[184:185], v[184:185], v[218:219]
	v_pk_add_f32 v[186:187], v[186:187], v[220:221]
	v_pk_add_f32 v[188:189], v[188:189], v[222:223]
	s_mov_b64 s[0:1], 0x1c01000
	v_lshl_add_u64 v[232:233], v[52:53], 0, s[0:1]
	global_load_dwordx4 v[208:211], v[232:233], off nt
	global_load_dwordx4 v[212:215], v[232:233], off offset:16 nt
	global_load_dwordx4 v[216:219], v[232:233], off offset:2048 nt
	global_load_dwordx4 v[220:223], v[232:233], off offset:2064 nt
	s_waitcnt vmcnt(8)
	v_pk_add_f32 v[174:175], v[174:175], v[224:225]
	v_pk_add_f32 v[176:177], v[176:177], v[226:227]
	v_pk_add_f32 v[178:179], v[178:179], v[228:229]
	v_pk_add_f32 v[180:181], v[180:181], v[230:231]
	v_pk_add_f32 v[182:183], v[182:183], v[238:239]
	v_pk_add_f32 v[184:185], v[184:185], v[240:241]
	v_pk_add_f32 v[186:187], v[186:187], v[242:243]
	v_pk_add_f32 v[188:189], v[188:189], v[244:245]
	global_load_dwordx4 v[224:227], v[76:77], off
	global_load_dwordx4 v[228:231], v[76:77], off offset:16
	global_load_dwordx4 v[238:241], v[78:79], off
	global_load_dwordx4 v[242:245], v[78:79], off offset:16
	s_waitcnt vmcnt(8)
	v_pk_add_f32 v[174:175], v[174:175], v[190:191]
	v_pk_add_f32 v[176:177], v[176:177], v[192:193]
	v_pk_add_f32 v[178:179], v[178:179], v[194:195]
	v_pk_add_f32 v[180:181], v[180:181], v[196:197]
	v_pk_add_f32 v[182:183], v[182:183], v[198:199]
	v_pk_add_f32 v[184:185], v[184:185], v[200:201]
	v_pk_add_f32 v[186:187], v[186:187], v[204:205]
	v_pk_add_f32 v[188:189], v[188:189], v[206:207]
	s_waitcnt vmcnt(4)
	v_pk_add_f32 v[174:175], v[174:175], v[208:209]
	v_pk_add_f32 v[176:177], v[176:177], v[210:211]
	v_pk_add_f32 v[178:179], v[178:179], v[212:213]
	v_pk_add_f32 v[180:181], v[180:181], v[214:215]
	v_pk_add_f32 v[182:183], v[182:183], v[216:217]
	v_pk_add_f32 v[184:185], v[184:185], v[218:219]
	v_pk_add_f32 v[186:187], v[186:187], v[220:221]
	v_pk_add_f32 v[188:189], v[188:189], v[222:223]
	s_waitcnt vmcnt(0)
	v_pk_fma_f32 v[60:61], v[174:175], v[224:225], v[60:61]
	v_pk_fma_f32 v[62:63], v[176:177], v[226:227], v[62:63]
	v_pk_fma_f32 v[58:59], v[178:179], v[228:229], v[58:59]
	v_pk_fma_f32 v[64:65], v[180:181], v[230:231], v[64:65]
	v_pk_fma_f32 v[54:55], v[182:183], v[238:239], v[54:55]
	v_pk_fma_f32 v[56:57], v[184:185], v[240:241], v[56:57]
	v_pk_fma_f32 v[32:33], v[186:187], v[242:243], v[32:33]
	v_pk_fma_f32 v[50:51], v[188:189], v[244:245], v[50:51]

.LBB0_1049:
	s_add_i32 s16, s8, s94
	s_cmpk_lt_i32 s16, 0x4200
	s_cselect_b64 s[14:15], -1, 0
	s_and_b64 s[0:1], s[14:15], exec
	s_cselect_b32 s10, s16, s8
	s_ashr_i32 s11, s10, 31
	s_lshl_b64 s[0:1], s[10:11], 12
	v_lshl_add_u64 v[32:33], v[80:81], 0, s[0:1]
	s_waitcnt vmcnt(4)
	global_load_dwordx4 v[62:65], v[32:33], off
	global_load_dwordx4 v[58:61], v[32:33], off offset:1024
	global_load_dwordx4 v[54:57], v[32:33], off offset:2048
	global_load_dwordx4 v[50:53], v[32:33], off offset:3072
	v_cvt_f32_f16_sdwa v167, v46 dst_sel:DWORD dst_unused:UNUSED_PAD src0_sel:WORD_1
	v_cvt_f32_f16_e32 v166, v46
	v_cvt_f32_f16_sdwa v163, v47 dst_sel:DWORD dst_unused:UNUSED_PAD src0_sel:WORD_1
	v_cvt_f32_f16_e32 v162, v47
	v_cvt_f32_f16_sdwa v161, v48 dst_sel:DWORD dst_unused:UNUSED_PAD src0_sel:WORD_1
	v_cvt_f32_f16_e32 v160, v48
	v_cvt_f32_f16_sdwa v165, v49 dst_sel:DWORD dst_unused:UNUSED_PAD src0_sel:WORD_1
	v_cvt_f32_f16_e32 v164, v49
	v_cvt_f32_f16_sdwa v155, v42 dst_sel:DWORD dst_unused:UNUSED_PAD src0_sel:WORD_1
	v_cvt_f32_f16_e32 v154, v42
	v_cvt_f32_f16_sdwa v157, v43 dst_sel:DWORD dst_unused:UNUSED_PAD src0_sel:WORD_1
	v_cvt_f32_f16_e32 v156, v43
	v_cvt_f32_f16_sdwa v153, v44 dst_sel:DWORD dst_unused:UNUSED_PAD src0_sel:WORD_1
	v_cvt_f32_f16_e32 v152, v44
	v_cvt_f32_f16_sdwa v159, v45 dst_sel:DWORD dst_unused:UNUSED_PAD src0_sel:WORD_1
	v_cvt_f32_f16_e32 v158, v45
	v_cvt_f32_f16_sdwa v45, v38 dst_sel:DWORD dst_unused:UNUSED_PAD src0_sel:WORD_1
	v_cvt_f32_f16_e32 v44, v38
	v_cvt_f32_f16_sdwa v47, v39 dst_sel:DWORD dst_unused:UNUSED_PAD src0_sel:WORD_1
	v_cvt_f32_f16_e32 v46, v39
	v_cvt_f32_f16_sdwa v43, v40 dst_sel:DWORD dst_unused:UNUSED_PAD src0_sel:WORD_1
	v_cvt_f32_f16_e32 v42, v40
	v_cvt_f32_f16_sdwa v49, v41 dst_sel:DWORD dst_unused:UNUSED_PAD src0_sel:WORD_1
	v_cvt_f32_f16_e32 v48, v41
	v_cvt_f32_f16_sdwa v39, v34 dst_sel:DWORD dst_unused:UNUSED_PAD src0_sel:WORD_1
	v_cvt_f32_f16_e32 v38, v34
	v_cvt_f32_f16_sdwa v41, v35 dst_sel:DWORD dst_unused:UNUSED_PAD src0_sel:WORD_1
	v_cvt_f32_f16_e32 v40, v35
	v_cvt_f32_f16_sdwa v33, v36 dst_sel:DWORD dst_unused:UNUSED_PAD src0_sel:WORD_1
	v_cvt_f32_f16_e32 v32, v36
	v_cvt_f32_f16_sdwa v35, v37 dst_sel:DWORD dst_unused:UNUSED_PAD src0_sel:WORD_1
	v_cvt_f32_f16_e32 v34, v37
	s_cmpk_gt_i32 s8, 0x3fff
	s_cselect_b64 s[2:3], -1, 0
	s_cmpk_lt_i32 s8, 0x4000
	s_cbranch_scc1 .LBB0_1051
	s_add_i32 s86, s8, 0xffffc000
	s_lshl_b64 s[0:1], s[86:87], 13
	v_lshl_add_u64 v[36:37], v[82:83], 0, s[0:1]
	global_load_dwordx4 v[190:193], v[36:37], off nt
	global_load_dwordx4 v[194:197], v[36:37], off offset:16 nt
	global_load_dwordx4 v[198:201], v[36:37], off offset:2048 nt
	global_load_dwordx4 v[204:207], v[36:37], off offset:2064 nt
	s_mov_b64 s[0:1], 0x400000
	v_lshl_add_u64 v[232:233], v[36:37], 0, s[0:1]
	global_load_dwordx4 v[208:211], v[232:233], off nt
	global_load_dwordx4 v[212:215], v[232:233], off offset:16 nt
	global_load_dwordx4 v[216:219], v[232:233], off offset:2048 nt
	global_load_dwordx4 v[220:223], v[232:233], off offset:2064 nt
	s_mov_b64 s[0:1], 0x800000
	v_lshl_add_u64 v[232:233], v[36:37], 0, s[0:1]
	global_load_dwordx4 v[224:227], v[232:233], off nt
	global_load_dwordx4 v[228:231], v[232:233], off offset:16 nt
	global_load_dwordx4 v[238:241], v[232:233], off offset:2048 nt
	global_load_dwordx4 v[242:245], v[232:233], off offset:2064 nt
	s_waitcnt vmcnt(8)
	v_mov_b64_e32 v[174:175], v[190:191]
	v_mov_b64_e32 v[176:177], v[192:193]
	v_mov_b64_e32 v[178:179], v[194:195]
	v_mov_b64_e32 v[180:181], v[196:197]
	v_mov_b64_e32 v[182:183], v[198:199]
	v_mov_b64_e32 v[184:185], v[200:201]
	v_mov_b64_e32 v[186:187], v[204:205]
	v_mov_b64_e32 v[188:189], v[206:207]
	s_mov_b64 s[0:1], 0xc00000
	v_lshl_add_u64 v[232:233], v[36:37], 0, s[0:1]
	global_load_dwordx4 v[190:193], v[232:233], off nt
	global_load_dwordx4 v[194:197], v[232:233], off offset:16 nt
	global_load_dwordx4 v[198:201], v[232:233], off offset:2048 nt
	global_load_dwordx4 v[204:207], v[232:233], off offset:2064 nt
	s_waitcnt vmcnt(8)
	v_pk_add_f32 v[174:175], v[174:175], v[208:209]
	v_pk_add_f32 v[176:177], v[176:177], v[210:211]
	v_pk_add_f32 v[178:179], v[178:179], v[212:213]
	v_pk_add_f32 v[180:181], v[180:181], v[214:215]
	v_pk_add_f32 v[182:183], v[182:183], v[216:217]
	v_pk_add_f32 v[184:185], v[184:185], v[218:219]
	v_pk_add_f32 v[186:187], v[186:187], v[220:221]
	v_pk_add_f32 v[188:189], v[188:189], v[222:223]
	s_mov_b64 s[0:1], 0x1000000
	v_lshl_add_u64 v[232:233], v[36:37], 0, s[0:1]
	global_load_dwordx4 v[208:211], v[232:233], off nt
	global_load_dwordx4 v[212:215], v[232:233], off offset:16 nt
	global_load_dwordx4 v[216:219], v[232:233], off offset:2048 nt
	global_load_dwordx4 v[220:223], v[232:233], off offset:2064 nt
	s_waitcnt vmcnt(8)
	v_pk_add_f32 v[174:175], v[174:175], v[224:225]
	v_pk_add_f32 v[176:177], v[176:177], v[226:227]
	v_pk_add_f32 v[178:179], v[178:179], v[228:229]
	v_pk_add_f32 v[180:181], v[180:181], v[230:231]
	v_pk_add_f32 v[182:183], v[182:183], v[238:239]
	v_pk_add_f32 v[184:185], v[184:185], v[240:241]
	v_pk_add_f32 v[186:187], v[186:187], v[242:243]
	v_pk_add_f32 v[188:189], v[188:189], v[244:245]
	s_mov_b64 s[0:1], 0x1400000
	v_lshl_add_u64 v[232:233], v[36:37], 0, s[0:1]
	global_load_dwordx4 v[224:227], v[232:233], off nt
	global_load_dwordx4 v[228:231], v[232:233], off offset:16 nt
	global_load_dwordx4 v[238:241], v[232:233], off offset:2048 nt
	global_load_dwordx4 v[242:245], v[232:233], off offset:2064 nt
	s_waitcnt vmcnt(8)
	v_pk_add_f32 v[174:175], v[174:175], v[190:191]
	v_pk_add_f32 v[176:177], v[176:177], v[192:193]
	v_pk_add_f32 v[178:179], v[178:179], v[194:195]
	v_pk_add_f32 v[180:181], v[180:181], v[196:197]
	v_pk_add_f32 v[182:183], v[182:183], v[198:199]
	v_pk_add_f32 v[184:185], v[184:185], v[200:201]
	v_pk_add_f32 v[186:187], v[186:187], v[204:205]
	v_pk_add_f32 v[188:189], v[188:189], v[206:207]
	s_mov_b64 s[0:1], 0x1800000
	v_lshl_add_u64 v[232:233], v[36:37], 0, s[0:1]
	global_load_dwordx4 v[190:193], v[232:233], off nt
	global_load_dwordx4 v[194:197], v[232:233], off offset:16 nt
	global_load_dwordx4 v[198:201], v[232:233], off offset:2048 nt
	global_load_dwordx4 v[204:207], v[232:233], off offset:2064 nt
	s_waitcnt vmcnt(8)
	v_pk_add_f32 v[174:175], v[174:175], v[208:209]
	v_pk_add_f32 v[176:177], v[176:177], v[210:211]
	v_pk_add_f32 v[178:179], v[178:179], v[212:213]
	v_pk_add_f32 v[180:181], v[180:181], v[214:215]
	v_pk_add_f32 v[182:183], v[182:183], v[216:217]
	v_pk_add_f32 v[184:185], v[184:185], v[218:219]
	v_pk_add_f32 v[186:187], v[186:187], v[220:221]
	v_pk_add_f32 v[188:189], v[188:189], v[222:223]
	s_mov_b64 s[0:1], 0x1c00000
	v_lshl_add_u64 v[232:233], v[36:37], 0, s[0:1]
	global_load_dwordx4 v[208:211], v[232:233], off nt
	global_load_dwordx4 v[212:215], v[232:233], off offset:16 nt
	global_load_dwordx4 v[216:219], v[232:233], off offset:2048 nt
	global_load_dwordx4 v[220:223], v[232:233], off offset:2064 nt
	s_waitcnt vmcnt(8)
	v_pk_add_f32 v[174:175], v[174:175], v[224:225]
	v_pk_add_f32 v[176:177], v[176:177], v[226:227]
	v_pk_add_f32 v[178:179], v[178:179], v[228:229]
	v_pk_add_f32 v[180:181], v[180:181], v[230:231]
	v_pk_add_f32 v[182:183], v[182:183], v[238:239]
	v_pk_add_f32 v[184:185], v[184:185], v[240:241]
	v_pk_add_f32 v[186:187], v[186:187], v[242:243]
	v_pk_add_f32 v[188:189], v[188:189], v[244:245]
	s_mov_b64 s[0:1], 0x2000000
	v_lshl_add_u64 v[232:233], v[36:37], 0, s[0:1]
	global_load_dwordx4 v[224:227], v[232:233], off nt
	global_load_dwordx4 v[228:231], v[232:233], off offset:16 nt
	global_load_dwordx4 v[238:241], v[232:233], off offset:2048 nt
	global_load_dwordx4 v[242:245], v[232:233], off offset:2064 nt
	s_waitcnt vmcnt(8)
	v_pk_add_f32 v[174:175], v[174:175], v[190:191]
	v_pk_add_f32 v[176:177], v[176:177], v[192:193]
	v_pk_add_f32 v[178:179], v[178:179], v[194:195]
	v_pk_add_f32 v[180:181], v[180:181], v[196:197]
	v_pk_add_f32 v[182:183], v[182:183], v[198:199]
	v_pk_add_f32 v[184:185], v[184:185], v[200:201]
	v_pk_add_f32 v[186:187], v[186:187], v[204:205]
	v_pk_add_f32 v[188:189], v[188:189], v[206:207]
	s_mov_b64 s[0:1], 0x2400000
	v_lshl_add_u64 v[232:233], v[36:37], 0, s[0:1]
	global_load_dwordx4 v[190:193], v[232:233], off nt
	global_load_dwordx4 v[194:197], v[232:233], off offset:16 nt
	global_load_dwordx4 v[198:201], v[232:233], off offset:2048 nt
	global_load_dwordx4 v[204:207], v[232:233], off offset:2064 nt
	s_waitcnt vmcnt(8)
	v_pk_add_f32 v[174:175], v[174:175], v[208:209]
	v_pk_add_f32 v[176:177], v[176:177], v[210:211]
	v_pk_add_f32 v[178:179], v[178:179], v[212:213]
	v_pk_add_f32 v[180:181], v[180:181], v[214:215]
	v_pk_add_f32 v[182:183], v[182:183], v[216:217]
	v_pk_add_f32 v[184:185], v[184:185], v[218:219]
	v_pk_add_f32 v[186:187], v[186:187], v[220:221]
	v_pk_add_f32 v[188:189], v[188:189], v[222:223]
	s_mov_b64 s[0:1], 0x2800000
	v_lshl_add_u64 v[232:233], v[36:37], 0, s[0:1]
	global_load_dwordx4 v[208:211], v[232:233], off nt
	global_load_dwordx4 v[212:215], v[232:233], off offset:16 nt
	global_load_dwordx4 v[216:219], v[232:233], off offset:2048 nt
	global_load_dwordx4 v[220:223], v[232:233], off offset:2064 nt
	s_waitcnt vmcnt(8)
	v_pk_add_f32 v[174:175], v[174:175], v[224:225]
	v_pk_add_f32 v[176:177], v[176:177], v[226:227]
	v_pk_add_f32 v[178:179], v[178:179], v[228:229]
	v_pk_add_f32 v[180:181], v[180:181], v[230:231]
	v_pk_add_f32 v[182:183], v[182:183], v[238:239]
	v_pk_add_f32 v[184:185], v[184:185], v[240:241]
	v_pk_add_f32 v[186:187], v[186:187], v[242:243]
	v_pk_add_f32 v[188:189], v[188:189], v[244:245]
	global_load_dwordx4 v[224:227], v[74:75], off
	global_load_dwordx4 v[228:231], v[74:75], off offset:16
	global_load_dwordx4 v[238:241], v[74:75], off offset:2048
	global_load_dwordx4 v[242:245], v[74:75], off offset:2064
	s_waitcnt vmcnt(8)
	v_pk_add_f32 v[174:175], v[174:175], v[190:191]
	v_pk_add_f32 v[176:177], v[176:177], v[192:193]
	v_pk_add_f32 v[178:179], v[178:179], v[194:195]
	v_pk_add_f32 v[180:181], v[180:181], v[196:197]
	v_pk_add_f32 v[182:183], v[182:183], v[198:199]
	v_pk_add_f32 v[184:185], v[184:185], v[200:201]
	v_pk_add_f32 v[186:187], v[186:187], v[204:205]
	v_pk_add_f32 v[188:189], v[188:189], v[206:207]
	s_mov_b64 s[0:1], 0x1000
	v_lshl_add_u64 v[232:233], v[36:37], 0, s[0:1]
	global_load_dwordx4 v[190:193], v[232:233], off nt
	global_load_dwordx4 v[194:197], v[232:233], off offset:16 nt
	global_load_dwordx4 v[198:201], v[232:233], off offset:2048 nt
	global_load_dwordx4 v[204:207], v[232:233], off offset:2064 nt
	s_waitcnt vmcnt(8)
	v_pk_add_f32 v[174:175], v[174:175], v[208:209]
	v_pk_add_f32 v[176:177], v[176:177], v[210:211]
	v_pk_add_f32 v[178:179], v[178:179], v[212:213]
	v_pk_add_f32 v[180:181], v[180:181], v[214:215]
	v_pk_add_f32 v[182:183], v[182:183], v[216:217]
	v_pk_add_f32 v[184:185], v[184:185], v[218:219]
	v_pk_add_f32 v[186:187], v[186:187], v[220:221]
	v_pk_add_f32 v[188:189], v[188:189], v[222:223]
	s_mov_b64 s[0:1], 0x401000
	v_lshl_add_u64 v[232:233], v[36:37], 0, s[0:1]
	global_load_dwordx4 v[208:211], v[232:233], off nt
	global_load_dwordx4 v[212:215], v[232:233], off offset:16 nt
	global_load_dwordx4 v[216:219], v[232:233], off offset:2048 nt
	global_load_dwordx4 v[220:223], v[232:233], off offset:2064 nt
	s_waitcnt vmcnt(8)
	v_pk_fma_f32 v[166:167], v[174:175], v[224:225], v[166:167]
	v_pk_fma_f32 v[162:163], v[176:177], v[226:227], v[162:163]
	v_pk_fma_f32 v[160:161], v[178:179], v[228:229], v[160:161]
	v_pk_fma_f32 v[164:165], v[180:181], v[230:231], v[164:165]
	v_pk_fma_f32 v[154:155], v[182:183], v[238:239], v[154:155]
	v_pk_fma_f32 v[156:157], v[184:185], v[240:241], v[156:157]
	v_pk_fma_f32 v[152:153], v[186:187], v[242:243], v[152:153]
	v_pk_fma_f32 v[158:159], v[188:189], v[244:245], v[158:159]
	s_mov_b64 s[0:1], 0x801000
	v_lshl_add_u64 v[232:233], v[36:37], 0, s[0:1]
	global_load_dwordx4 v[224:227], v[232:233], off nt
	global_load_dwordx4 v[228:231], v[232:233], off offset:16 nt
	global_load_dwordx4 v[238:241], v[232:233], off offset:2048 nt
	global_load_dwordx4 v[242:245], v[232:233], off offset:2064 nt
	s_waitcnt vmcnt(8)
	v_mov_b64_e32 v[174:175], v[190:191]
	v_mov_b64_e32 v[176:177], v[192:193]
	v_mov_b64_e32 v[178:179], v[194:195]
	v_mov_b64_e32 v[180:181], v[196:197]
	v_mov_b64_e32 v[182:183], v[198:199]
	v_mov_b64_e32 v[184:185], v[200:201]
	v_mov_b64_e32 v[186:187], v[204:205]
	v_mov_b64_e32 v[188:189], v[206:207]
	s_mov_b64 s[0:1], 0xc01000
	v_lshl_add_u64 v[232:233], v[36:37], 0, s[0:1]
	global_load_dwordx4 v[190:193], v[232:233], off nt
	global_load_dwordx4 v[194:197], v[232:233], off offset:16 nt
	global_load_dwordx4 v[198:201], v[232:233], off offset:2048 nt
	global_load_dwordx4 v[204:207], v[232:233], off offset:2064 nt
	s_waitcnt vmcnt(8)
	v_pk_add_f32 v[174:175], v[174:175], v[208:209]
	v_pk_add_f32 v[176:177], v[176:177], v[210:211]
	v_pk_add_f32 v[178:179], v[178:179], v[212:213]
	v_pk_add_f32 v[180:181], v[180:181], v[214:215]
	v_pk_add_f32 v[182:183], v[182:183], v[216:217]
	v_pk_add_f32 v[184:185], v[184:185], v[218:219]
	v_pk_add_f32 v[186:187], v[186:187], v[220:221]
	v_pk_add_f32 v[188:189], v[188:189], v[222:223]
	s_mov_b64 s[0:1], 0x1001000
	v_lshl_add_u64 v[232:233], v[36:37], 0, s[0:1]
	global_load_dwordx4 v[208:211], v[232:233], off nt
	global_load_dwordx4 v[212:215], v[232:233], off offset:16 nt
	global_load_dwordx4 v[216:219], v[232:233], off offset:2048 nt
	global_load_dwordx4 v[220:223], v[232:233], off offset:2064 nt
	s_waitcnt vmcnt(8)
	v_pk_add_f32 v[174:175], v[174:175], v[224:225]
	v_pk_add_f32 v[176:177], v[176:177], v[226:227]
	v_pk_add_f32 v[178:179], v[178:179], v[228:229]
	v_pk_add_f32 v[180:181], v[180:181], v[230:231]
	v_pk_add_f32 v[182:183], v[182:183], v[238:239]
	v_pk_add_f32 v[184:185], v[184:185], v[240:241]
	v_pk_add_f32 v[186:187], v[186:187], v[242:243]
	v_pk_add_f32 v[188:189], v[188:189], v[244:245]
	s_mov_b64 s[0:1], 0x1401000
	v_lshl_add_u64 v[232:233], v[36:37], 0, s[0:1]
	global_load_dwordx4 v[224:227], v[232:233], off nt
	global_load_dwordx4 v[228:231], v[232:233], off offset:16 nt
	global_load_dwordx4 v[238:241], v[232:233], off offset:2048 nt
	global_load_dwordx4 v[242:245], v[232:233], off offset:2064 nt
	s_waitcnt vmcnt(8)
	v_pk_add_f32 v[174:175], v[174:175], v[190:191]
	v_pk_add_f32 v[176:177], v[176:177], v[192:193]
	v_pk_add_f32 v[178:179], v[178:179], v[194:195]
	v_pk_add_f32 v[180:181], v[180:181], v[196:197]
	v_pk_add_f32 v[182:183], v[182:183], v[198:199]
	v_pk_add_f32 v[184:185], v[184:185], v[200:201]
	v_pk_add_f32 v[186:187], v[186:187], v[204:205]
	v_pk_add_f32 v[188:189], v[188:189], v[206:207]
	s_mov_b64 s[0:1], 0x1801000
	v_lshl_add_u64 v[232:233], v[36:37], 0, s[0:1]
	global_load_dwordx4 v[190:193], v[232:233], off nt
	global_load_dwordx4 v[194:197], v[232:233], off offset:16 nt
	global_load_dwordx4 v[198:201], v[232:233], off offset:2048 nt
	global_load_dwordx4 v[204:207], v[232:233], off offset:2064 nt
	s_waitcnt vmcnt(8)
	v_pk_add_f32 v[174:175], v[174:175], v[208:209]
	v_pk_add_f32 v[176:177], v[176:177], v[210:211]
	v_pk_add_f32 v[178:179], v[178:179], v[212:213]
	v_pk_add_f32 v[180:181], v[180:181], v[214:215]
	v_pk_add_f32 v[182:183], v[182:183], v[216:217]
	v_pk_add_f32 v[184:185], v[184:185], v[218:219]
	v_pk_add_f32 v[186:187], v[186:187], v[220:221]
	v_pk_add_f32 v[188:189], v[188:189], v[222:223]
	s_mov_b64 s[0:1], 0x1c01000
	v_lshl_add_u64 v[232:233], v[36:37], 0, s[0:1]
	global_load_dwordx4 v[208:211], v[232:233], off nt
	global_load_dwordx4 v[212:215], v[232:233], off offset:16 nt
	global_load_dwordx4 v[216:219], v[232:233], off offset:2048 nt
	global_load_dwordx4 v[220:223], v[232:233], off offset:2064 nt
	s_waitcnt vmcnt(8)
	v_pk_add_f32 v[174:175], v[174:175], v[224:225]
	v_pk_add_f32 v[176:177], v[176:177], v[226:227]
	v_pk_add_f32 v[178:179], v[178:179], v[228:229]
	v_pk_add_f32 v[180:181], v[180:181], v[230:231]
	v_pk_add_f32 v[182:183], v[182:183], v[238:239]
	v_pk_add_f32 v[184:185], v[184:185], v[240:241]
	v_pk_add_f32 v[186:187], v[186:187], v[242:243]
	v_pk_add_f32 v[188:189], v[188:189], v[244:245]
	s_mov_b64 s[0:1], 0x2001000
	v_lshl_add_u64 v[232:233], v[36:37], 0, s[0:1]
	global_load_dwordx4 v[224:227], v[232:233], off nt
	global_load_dwordx4 v[228:231], v[232:233], off offset:16 nt
	global_load_dwordx4 v[238:241], v[232:233], off offset:2048 nt
	global_load_dwordx4 v[242:245], v[232:233], off offset:2064 nt
	s_waitcnt vmcnt(8)
	v_pk_add_f32 v[174:175], v[174:175], v[190:191]
	v_pk_add_f32 v[176:177], v[176:177], v[192:193]
	v_pk_add_f32 v[178:179], v[178:179], v[194:195]
	v_pk_add_f32 v[180:181], v[180:181], v[196:197]
	v_pk_add_f32 v[182:183], v[182:183], v[198:199]
	v_pk_add_f32 v[184:185], v[184:185], v[200:201]
	v_pk_add_f32 v[186:187], v[186:187], v[204:205]
	v_pk_add_f32 v[188:189], v[188:189], v[206:207]
	s_mov_b64 s[0:1], 0x2401000
	v_lshl_add_u64 v[232:233], v[36:37], 0, s[0:1]
	global_load_dwordx4 v[190:193], v[232:233], off nt
	global_load_dwordx4 v[194:197], v[232:233], off offset:16 nt
	global_load_dwordx4 v[198:201], v[232:233], off offset:2048 nt
	global_load_dwordx4 v[204:207], v[232:233], off offset:2064 nt
	s_waitcnt vmcnt(8)
	v_pk_add_f32 v[174:175], v[174:175], v[208:209]
	v_pk_add_f32 v[176:177], v[176:177], v[210:211]
	v_pk_add_f32 v[178:179], v[178:179], v[212:213]
	v_pk_add_f32 v[180:181], v[180:181], v[214:215]
	v_pk_add_f32 v[182:183], v[182:183], v[216:217]
	v_pk_add_f32 v[184:185], v[184:185], v[218:219]
	v_pk_add_f32 v[186:187], v[186:187], v[220:221]
	v_pk_add_f32 v[188:189], v[188:189], v[222:223]
	s_mov_b64 s[0:1], 0x2801000
	v_lshl_add_u64 v[232:233], v[36:37], 0, s[0:1]
	global_load_dwordx4 v[208:211], v[232:233], off nt
	global_load_dwordx4 v[212:215], v[232:233], off offset:16 nt
	global_load_dwordx4 v[216:219], v[232:233], off offset:2048 nt
	global_load_dwordx4 v[220:223], v[232:233], off offset:2064 nt
	s_waitcnt vmcnt(8)
	v_pk_add_f32 v[174:175], v[174:175], v[224:225]
	v_pk_add_f32 v[176:177], v[176:177], v[226:227]
	v_pk_add_f32 v[178:179], v[178:179], v[228:229]
	v_pk_add_f32 v[180:181], v[180:181], v[230:231]
	v_pk_add_f32 v[182:183], v[182:183], v[238:239]
	v_pk_add_f32 v[184:185], v[184:185], v[240:241]
	v_pk_add_f32 v[186:187], v[186:187], v[242:243]
	v_pk_add_f32 v[188:189], v[188:189], v[244:245]
	global_load_dwordx4 v[224:227], v[76:77], off
	global_load_dwordx4 v[228:231], v[76:77], off offset:16
	global_load_dwordx4 v[238:241], v[78:79], off
	global_load_dwordx4 v[242:245], v[78:79], off offset:16
	s_waitcnt vmcnt(8)
	v_pk_add_f32 v[174:175], v[174:175], v[190:191]
	v_pk_add_f32 v[176:177], v[176:177], v[192:193]
	v_pk_add_f32 v[178:179], v[178:179], v[194:195]
	v_pk_add_f32 v[180:181], v[180:181], v[196:197]
	v_pk_add_f32 v[182:183], v[182:183], v[198:199]
	v_pk_add_f32 v[184:185], v[184:185], v[200:201]
	v_pk_add_f32 v[186:187], v[186:187], v[204:205]
	v_pk_add_f32 v[188:189], v[188:189], v[206:207]
	s_waitcnt vmcnt(4)
	v_pk_add_f32 v[174:175], v[174:175], v[208:209]
	v_pk_add_f32 v[176:177], v[176:177], v[210:211]
	v_pk_add_f32 v[178:179], v[178:179], v[212:213]
	v_pk_add_f32 v[180:181], v[180:181], v[214:215]
	v_pk_add_f32 v[182:183], v[182:183], v[216:217]
	v_pk_add_f32 v[184:185], v[184:185], v[218:219]
	v_pk_add_f32 v[186:187], v[186:187], v[220:221]
	v_pk_add_f32 v[188:189], v[188:189], v[222:223]
	s_waitcnt vmcnt(0)
	v_pk_fma_f32 v[44:45], v[174:175], v[224:225], v[44:45]
	v_pk_fma_f32 v[46:47], v[176:177], v[226:227], v[46:47]
	v_pk_fma_f32 v[42:43], v[178:179], v[228:229], v[42:43]
	v_pk_fma_f32 v[48:49], v[180:181], v[230:231], v[48:49]
	v_pk_fma_f32 v[38:39], v[182:183], v[238:239], v[38:39]
	v_pk_fma_f32 v[40:41], v[184:185], v[240:241], v[40:41]
	v_pk_fma_f32 v[32:33], v[186:187], v[242:243], v[32:33]
	v_pk_fma_f32 v[34:35], v[188:189], v[244:245], v[34:35]

.LBB0_1055:
	s_add_i32 s0, s75, s8
	s_cmpk_lt_i32 s0, 0x4200
	s_cselect_b32 s0, s0, s8
	s_ashr_i32 s1, s0, 31
	s_lshl_b64 s[0:1], s[0:1], 12
	v_lshl_add_u64 v[32:33], v[80:81], 0, s[0:1]
	global_load_dwordx4 v[46:49], v[32:33], off
	global_load_dwordx4 v[42:45], v[32:33], off offset:1024
	global_load_dwordx4 v[38:41], v[32:33], off offset:2048
	global_load_dwordx4 v[34:37], v[32:33], off offset:3072
	s_waitcnt vmcnt(8)
	s_andn2_b64 vcc, exec, s[14:15]
	s_cbranch_vccnz .LBB0_1045
	v_cvt_f32_f16_sdwa v167, v62 dst_sel:DWORD dst_unused:UNUSED_PAD src0_sel:WORD_1
	v_cvt_f32_f16_e32 v166, v62
	v_cvt_f32_f16_sdwa v163, v63 dst_sel:DWORD dst_unused:UNUSED_PAD src0_sel:WORD_1
	v_cvt_f32_f16_e32 v162, v63
	v_cvt_f32_f16_sdwa v161, v64 dst_sel:DWORD dst_unused:UNUSED_PAD src0_sel:WORD_1
	v_cvt_f32_f16_e32 v160, v64
	v_cvt_f32_f16_sdwa v165, v65 dst_sel:DWORD dst_unused:UNUSED_PAD src0_sel:WORD_1
	v_cvt_f32_f16_e32 v164, v65
	v_cvt_f32_f16_sdwa v155, v58 dst_sel:DWORD dst_unused:UNUSED_PAD src0_sel:WORD_1
	v_cvt_f32_f16_e32 v154, v58
	v_cvt_f32_f16_sdwa v157, v59 dst_sel:DWORD dst_unused:UNUSED_PAD src0_sel:WORD_1
	v_cvt_f32_f16_e32 v156, v59
	v_cvt_f32_f16_sdwa v153, v60 dst_sel:DWORD dst_unused:UNUSED_PAD src0_sel:WORD_1
	v_cvt_f32_f16_e32 v152, v60
	v_cvt_f32_f16_sdwa v159, v61 dst_sel:DWORD dst_unused:UNUSED_PAD src0_sel:WORD_1
	v_cvt_f32_f16_e32 v158, v61
	v_cvt_f32_f16_sdwa v61, v54 dst_sel:DWORD dst_unused:UNUSED_PAD src0_sel:WORD_1
	v_cvt_f32_f16_e32 v60, v54
	v_cvt_f32_f16_sdwa v63, v55 dst_sel:DWORD dst_unused:UNUSED_PAD src0_sel:WORD_1
	v_cvt_f32_f16_e32 v62, v55
	v_cvt_f32_f16_sdwa v59, v56 dst_sel:DWORD dst_unused:UNUSED_PAD src0_sel:WORD_1
	v_cvt_f32_f16_e32 v58, v56
	v_cvt_f32_f16_sdwa v65, v57 dst_sel:DWORD dst_unused:UNUSED_PAD src0_sel:WORD_1
	v_cvt_f32_f16_e32 v64, v57
	v_cvt_f32_f16_sdwa v55, v50 dst_sel:DWORD dst_unused:UNUSED_PAD src0_sel:WORD_1
	v_cvt_f32_f16_e32 v54, v50
	v_cvt_f32_f16_sdwa v57, v51 dst_sel:DWORD dst_unused:UNUSED_PAD src0_sel:WORD_1
	v_cvt_f32_f16_e32 v56, v51
	v_cvt_f32_f16_sdwa v33, v52 dst_sel:DWORD dst_unused:UNUSED_PAD src0_sel:WORD_1
	v_cvt_f32_f16_e32 v32, v52
	v_cvt_f32_f16_sdwa v51, v53 dst_sel:DWORD dst_unused:UNUSED_PAD src0_sel:WORD_1
	v_cvt_f32_f16_e32 v50, v53
	s_cmpk_gt_i32 s16, 0x3fff
	s_cselect_b64 s[2:3], -1, 0
	s_cmpk_lt_i32 s16, 0x4000
	s_cbranch_scc1 .LBB0_1058
	s_add_i32 s86, s16, 0xffffc000
	s_lshl_b64 s[0:1], s[86:87], 13
	v_lshl_add_u64 v[52:53], v[82:83], 0, s[0:1]
	global_load_dwordx4 v[190:193], v[52:53], off nt
	global_load_dwordx4 v[194:197], v[52:53], off offset:16 nt
	global_load_dwordx4 v[198:201], v[52:53], off offset:2048 nt
	global_load_dwordx4 v[204:207], v[52:53], off offset:2064 nt
	s_mov_b64 s[0:1], 0x400000
	v_lshl_add_u64 v[232:233], v[52:53], 0, s[0:1]
	global_load_dwordx4 v[208:211], v[232:233], off nt
	global_load_dwordx4 v[212:215], v[232:233], off offset:16 nt
	global_load_dwordx4 v[216:219], v[232:233], off offset:2048 nt
	global_load_dwordx4 v[220:223], v[232:233], off offset:2064 nt
	s_mov_b64 s[0:1], 0x800000
	v_lshl_add_u64 v[232:233], v[52:53], 0, s[0:1]
	global_load_dwordx4 v[224:227], v[232:233], off nt
	global_load_dwordx4 v[228:231], v[232:233], off offset:16 nt
	global_load_dwordx4 v[238:241], v[232:233], off offset:2048 nt
	global_load_dwordx4 v[242:245], v[232:233], off offset:2064 nt
	s_waitcnt vmcnt(8)
	v_mov_b64_e32 v[174:175], v[190:191]
	v_mov_b64_e32 v[176:177], v[192:193]
	v_mov_b64_e32 v[178:179], v[194:195]
	v_mov_b64_e32 v[180:181], v[196:197]
	v_mov_b64_e32 v[182:183], v[198:199]
	v_mov_b64_e32 v[184:185], v[200:201]
	v_mov_b64_e32 v[186:187], v[204:205]
	v_mov_b64_e32 v[188:189], v[206:207]
	s_mov_b64 s[0:1], 0xc00000
	v_lshl_add_u64 v[232:233], v[52:53], 0, s[0:1]
	global_load_dwordx4 v[190:193], v[232:233], off nt
	global_load_dwordx4 v[194:197], v[232:233], off offset:16 nt
	global_load_dwordx4 v[198:201], v[232:233], off offset:2048 nt
	global_load_dwordx4 v[204:207], v[232:233], off offset:2064 nt
	s_waitcnt vmcnt(8)
	v_pk_add_f32 v[174:175], v[174:175], v[208:209]
	v_pk_add_f32 v[176:177], v[176:177], v[210:211]
	v_pk_add_f32 v[178:179], v[178:179], v[212:213]
	v_pk_add_f32 v[180:181], v[180:181], v[214:215]
	v_pk_add_f32 v[182:183], v[182:183], v[216:217]
	v_pk_add_f32 v[184:185], v[184:185], v[218:219]
	v_pk_add_f32 v[186:187], v[186:187], v[220:221]
	v_pk_add_f32 v[188:189], v[188:189], v[222:223]
	s_mov_b64 s[0:1], 0x1000000
	v_lshl_add_u64 v[232:233], v[52:53], 0, s[0:1]
	global_load_dwordx4 v[208:211], v[232:233], off nt
	global_load_dwordx4 v[212:215], v[232:233], off offset:16 nt
	global_load_dwordx4 v[216:219], v[232:233], off offset:2048 nt
	global_load_dwordx4 v[220:223], v[232:233], off offset:2064 nt
	s_waitcnt vmcnt(8)
	v_pk_add_f32 v[174:175], v[174:175], v[224:225]
	v_pk_add_f32 v[176:177], v[176:177], v[226:227]
	v_pk_add_f32 v[178:179], v[178:179], v[228:229]
	v_pk_add_f32 v[180:181], v[180:181], v[230:231]
	v_pk_add_f32 v[182:183], v[182:183], v[238:239]
	v_pk_add_f32 v[184:185], v[184:185], v[240:241]
	v_pk_add_f32 v[186:187], v[186:187], v[242:243]
	v_pk_add_f32 v[188:189], v[188:189], v[244:245]
	s_mov_b64 s[0:1], 0x1400000
	v_lshl_add_u64 v[232:233], v[52:53], 0, s[0:1]
	global_load_dwordx4 v[224:227], v[232:233], off nt
	global_load_dwordx4 v[228:231], v[232:233], off offset:16 nt
	global_load_dwordx4 v[238:241], v[232:233], off offset:2048 nt
	global_load_dwordx4 v[242:245], v[232:233], off offset:2064 nt
	s_waitcnt vmcnt(8)
	v_pk_add_f32 v[174:175], v[174:175], v[190:191]
	v_pk_add_f32 v[176:177], v[176:177], v[192:193]
	v_pk_add_f32 v[178:179], v[178:179], v[194:195]
	v_pk_add_f32 v[180:181], v[180:181], v[196:197]
	v_pk_add_f32 v[182:183], v[182:183], v[198:199]
	v_pk_add_f32 v[184:185], v[184:185], v[200:201]
	v_pk_add_f32 v[186:187], v[186:187], v[204:205]
	v_pk_add_f32 v[188:189], v[188:189], v[206:207]
	s_mov_b64 s[0:1], 0x1800000
	v_lshl_add_u64 v[232:233], v[52:53], 0, s[0:1]
	global_load_dwordx4 v[190:193], v[232:233], off nt
	global_load_dwordx4 v[194:197], v[232:233], off offset:16 nt
	global_load_dwordx4 v[198:201], v[232:233], off offset:2048 nt
	global_load_dwordx4 v[204:207], v[232:233], off offset:2064 nt
	s_waitcnt vmcnt(8)
	v_pk_add_f32 v[174:175], v[174:175], v[208:209]
	v_pk_add_f32 v[176:177], v[176:177], v[210:211]
	v_pk_add_f32 v[178:179], v[178:179], v[212:213]
	v_pk_add_f32 v[180:181], v[180:181], v[214:215]
	v_pk_add_f32 v[182:183], v[182:183], v[216:217]
	v_pk_add_f32 v[184:185], v[184:185], v[218:219]
	v_pk_add_f32 v[186:187], v[186:187], v[220:221]
	v_pk_add_f32 v[188:189], v[188:189], v[222:223]
	s_mov_b64 s[0:1], 0x1c00000
	v_lshl_add_u64 v[232:233], v[52:53], 0, s[0:1]
	global_load_dwordx4 v[208:211], v[232:233], off nt
	global_load_dwordx4 v[212:215], v[232:233], off offset:16 nt
	global_load_dwordx4 v[216:219], v[232:233], off offset:2048 nt
	global_load_dwordx4 v[220:223], v[232:233], off offset:2064 nt
	s_waitcnt vmcnt(8)
	v_pk_add_f32 v[174:175], v[174:175], v[224:225]
	v_pk_add_f32 v[176:177], v[176:177], v[226:227]
	v_pk_add_f32 v[178:179], v[178:179], v[228:229]
	v_pk_add_f32 v[180:181], v[180:181], v[230:231]
	v_pk_add_f32 v[182:183], v[182:183], v[238:239]
	v_pk_add_f32 v[184:185], v[184:185], v[240:241]
	v_pk_add_f32 v[186:187], v[186:187], v[242:243]
	v_pk_add_f32 v[188:189], v[188:189], v[244:245]
	s_mov_b64 s[0:1], 0x2000000
	v_lshl_add_u64 v[232:233], v[52:53], 0, s[0:1]
	global_load_dwordx4 v[224:227], v[232:233], off nt
	global_load_dwordx4 v[228:231], v[232:233], off offset:16 nt
	global_load_dwordx4 v[238:241], v[232:233], off offset:2048 nt
	global_load_dwordx4 v[242:245], v[232:233], off offset:2064 nt
	s_waitcnt vmcnt(8)
	v_pk_add_f32 v[174:175], v[174:175], v[190:191]
	v_pk_add_f32 v[176:177], v[176:177], v[192:193]
	v_pk_add_f32 v[178:179], v[178:179], v[194:195]
	v_pk_add_f32 v[180:181], v[180:181], v[196:197]
	v_pk_add_f32 v[182:183], v[182:183], v[198:199]
	v_pk_add_f32 v[184:185], v[184:185], v[200:201]
	v_pk_add_f32 v[186:187], v[186:187], v[204:205]
	v_pk_add_f32 v[188:189], v[188:189], v[206:207]
	s_mov_b64 s[0:1], 0x2400000
	v_lshl_add_u64 v[232:233], v[52:53], 0, s[0:1]
	global_load_dwordx4 v[190:193], v[232:233], off nt
	global_load_dwordx4 v[194:197], v[232:233], off offset:16 nt
	global_load_dwordx4 v[198:201], v[232:233], off offset:2048 nt
	global_load_dwordx4 v[204:207], v[232:233], off offset:2064 nt
	s_waitcnt vmcnt(8)
	v_pk_add_f32 v[174:175], v[174:175], v[208:209]
	v_pk_add_f32 v[176:177], v[176:177], v[210:211]
	v_pk_add_f32 v[178:179], v[178:179], v[212:213]
	v_pk_add_f32 v[180:181], v[180:181], v[214:215]
	v_pk_add_f32 v[182:183], v[182:183], v[216:217]
	v_pk_add_f32 v[184:185], v[184:185], v[218:219]
	v_pk_add_f32 v[186:187], v[186:187], v[220:221]
	v_pk_add_f32 v[188:189], v[188:189], v[222:223]
	s_mov_b64 s[0:1], 0x2800000
	v_lshl_add_u64 v[232:233], v[52:53], 0, s[0:1]
	global_load_dwordx4 v[208:211], v[232:233], off nt
	global_load_dwordx4 v[212:215], v[232:233], off offset:16 nt
	global_load_dwordx4 v[216:219], v[232:233], off offset:2048 nt
	global_load_dwordx4 v[220:223], v[232:233], off offset:2064 nt
	s_waitcnt vmcnt(8)
	v_pk_add_f32 v[174:175], v[174:175], v[224:225]
	v_pk_add_f32 v[176:177], v[176:177], v[226:227]
	v_pk_add_f32 v[178:179], v[178:179], v[228:229]
	v_pk_add_f32 v[180:181], v[180:181], v[230:231]
	v_pk_add_f32 v[182:183], v[182:183], v[238:239]
	v_pk_add_f32 v[184:185], v[184:185], v[240:241]
	v_pk_add_f32 v[186:187], v[186:187], v[242:243]
	v_pk_add_f32 v[188:189], v[188:189], v[244:245]
	global_load_dwordx4 v[224:227], v[74:75], off
	global_load_dwordx4 v[228:231], v[74:75], off offset:16
	global_load_dwordx4 v[238:241], v[74:75], off offset:2048
	global_load_dwordx4 v[242:245], v[74:75], off offset:2064
	s_waitcnt vmcnt(8)
	v_pk_add_f32 v[174:175], v[174:175], v[190:191]
	v_pk_add_f32 v[176:177], v[176:177], v[192:193]
	v_pk_add_f32 v[178:179], v[178:179], v[194:195]
	v_pk_add_f32 v[180:181], v[180:181], v[196:197]
	v_pk_add_f32 v[182:183], v[182:183], v[198:199]
	v_pk_add_f32 v[184:185], v[184:185], v[200:201]
	v_pk_add_f32 v[186:187], v[186:187], v[204:205]
	v_pk_add_f32 v[188:189], v[188:189], v[206:207]
	s_mov_b64 s[0:1], 0x1000
	v_lshl_add_u64 v[232:233], v[52:53], 0, s[0:1]
	global_load_dwordx4 v[190:193], v[232:233], off nt
	global_load_dwordx4 v[194:197], v[232:233], off offset:16 nt
	global_load_dwordx4 v[198:201], v[232:233], off offset:2048 nt
	global_load_dwordx4 v[204:207], v[232:233], off offset:2064 nt
	s_waitcnt vmcnt(8)
	v_pk_add_f32 v[174:175], v[174:175], v[208:209]
	v_pk_add_f32 v[176:177], v[176:177], v[210:211]
	v_pk_add_f32 v[178:179], v[178:179], v[212:213]
	v_pk_add_f32 v[180:181], v[180:181], v[214:215]
	v_pk_add_f32 v[182:183], v[182:183], v[216:217]
	v_pk_add_f32 v[184:185], v[184:185], v[218:219]
	v_pk_add_f32 v[186:187], v[186:187], v[220:221]
	v_pk_add_f32 v[188:189], v[188:189], v[222:223]
	s_mov_b64 s[0:1], 0x401000
	v_lshl_add_u64 v[232:233], v[52:53], 0, s[0:1]
	global_load_dwordx4 v[208:211], v[232:233], off nt
	global_load_dwordx4 v[212:215], v[232:233], off offset:16 nt
	global_load_dwordx4 v[216:219], v[232:233], off offset:2048 nt
	global_load_dwordx4 v[220:223], v[232:233], off offset:2064 nt
	s_waitcnt vmcnt(8)
	v_pk_fma_f32 v[166:167], v[174:175], v[224:225], v[166:167]
	v_pk_fma_f32 v[162:163], v[176:177], v[226:227], v[162:163]
	v_pk_fma_f32 v[160:161], v[178:179], v[228:229], v[160:161]
	v_pk_fma_f32 v[164:165], v[180:181], v[230:231], v[164:165]
	v_pk_fma_f32 v[154:155], v[182:183], v[238:239], v[154:155]
	v_pk_fma_f32 v[156:157], v[184:185], v[240:241], v[156:157]
	v_pk_fma_f32 v[152:153], v[186:187], v[242:243], v[152:153]
	v_pk_fma_f32 v[158:159], v[188:189], v[244:245], v[158:159]
	s_mov_b64 s[0:1], 0x801000
	v_lshl_add_u64 v[232:233], v[52:53], 0, s[0:1]
	global_load_dwordx4 v[224:227], v[232:233], off nt
	global_load_dwordx4 v[228:231], v[232:233], off offset:16 nt
	global_load_dwordx4 v[238:241], v[232:233], off offset:2048 nt
	global_load_dwordx4 v[242:245], v[232:233], off offset:2064 nt
	s_waitcnt vmcnt(8)
	v_mov_b64_e32 v[174:175], v[190:191]
	v_mov_b64_e32 v[176:177], v[192:193]
	v_mov_b64_e32 v[178:179], v[194:195]
	v_mov_b64_e32 v[180:181], v[196:197]
	v_mov_b64_e32 v[182:183], v[198:199]
	v_mov_b64_e32 v[184:185], v[200:201]
	v_mov_b64_e32 v[186:187], v[204:205]
	v_mov_b64_e32 v[188:189], v[206:207]
	s_mov_b64 s[0:1], 0xc01000
	v_lshl_add_u64 v[232:233], v[52:53], 0, s[0:1]
	global_load_dwordx4 v[190:193], v[232:233], off nt
	global_load_dwordx4 v[194:197], v[232:233], off offset:16 nt
	global_load_dwordx4 v[198:201], v[232:233], off offset:2048 nt
	global_load_dwordx4 v[204:207], v[232:233], off offset:2064 nt
	s_waitcnt vmcnt(8)
	v_pk_add_f32 v[174:175], v[174:175], v[208:209]
	v_pk_add_f32 v[176:177], v[176:177], v[210:211]
	v_pk_add_f32 v[178:179], v[178:179], v[212:213]
	v_pk_add_f32 v[180:181], v[180:181], v[214:215]
	v_pk_add_f32 v[182:183], v[182:183], v[216:217]
	v_pk_add_f32 v[184:185], v[184:185], v[218:219]
	v_pk_add_f32 v[186:187], v[186:187], v[220:221]
	v_pk_add_f32 v[188:189], v[188:189], v[222:223]
	s_mov_b64 s[0:1], 0x1001000
	v_lshl_add_u64 v[232:233], v[52:53], 0, s[0:1]
	global_load_dwordx4 v[208:211], v[232:233], off nt
	global_load_dwordx4 v[212:215], v[232:233], off offset:16 nt
	global_load_dwordx4 v[216:219], v[232:233], off offset:2048 nt
	global_load_dwordx4 v[220:223], v[232:233], off offset:2064 nt
	s_waitcnt vmcnt(8)
	v_pk_add_f32 v[174:175], v[174:175], v[224:225]
	v_pk_add_f32 v[176:177], v[176:177], v[226:227]
	v_pk_add_f32 v[178:179], v[178:179], v[228:229]
	v_pk_add_f32 v[180:181], v[180:181], v[230:231]
	v_pk_add_f32 v[182:183], v[182:183], v[238:239]
	v_pk_add_f32 v[184:185], v[184:185], v[240:241]
	v_pk_add_f32 v[186:187], v[186:187], v[242:243]
	v_pk_add_f32 v[188:189], v[188:189], v[244:245]
	s_mov_b64 s[0:1], 0x1401000
	v_lshl_add_u64 v[232:233], v[52:53], 0, s[0:1]
	global_load_dwordx4 v[224:227], v[232:233], off nt
	global_load_dwordx4 v[228:231], v[232:233], off offset:16 nt
	global_load_dwordx4 v[238:241], v[232:233], off offset:2048 nt
	global_load_dwordx4 v[242:245], v[232:233], off offset:2064 nt
	s_waitcnt vmcnt(8)
	v_pk_add_f32 v[174:175], v[174:175], v[190:191]
	v_pk_add_f32 v[176:177], v[176:177], v[192:193]
	v_pk_add_f32 v[178:179], v[178:179], v[194:195]
	v_pk_add_f32 v[180:181], v[180:181], v[196:197]
	v_pk_add_f32 v[182:183], v[182:183], v[198:199]
	v_pk_add_f32 v[184:185], v[184:185], v[200:201]
	v_pk_add_f32 v[186:187], v[186:187], v[204:205]
	v_pk_add_f32 v[188:189], v[188:189], v[206:207]
	s_mov_b64 s[0:1], 0x1801000
	v_lshl_add_u64 v[232:233], v[52:53], 0, s[0:1]
	global_load_dwordx4 v[190:193], v[232:233], off nt
	global_load_dwordx4 v[194:197], v[232:233], off offset:16 nt
	global_load_dwordx4 v[198:201], v[232:233], off offset:2048 nt
	global_load_dwordx4 v[204:207], v[232:233], off offset:2064 nt
	s_waitcnt vmcnt(8)
	v_pk_add_f32 v[174:175], v[174:175], v[208:209]
	v_pk_add_f32 v[176:177], v[176:177], v[210:211]
	v_pk_add_f32 v[178:179], v[178:179], v[212:213]
	v_pk_add_f32 v[180:181], v[180:181], v[214:215]
	v_pk_add_f32 v[182:183], v[182:183], v[216:217]
	v_pk_add_f32 v[184:185], v[184:185], v[218:219]
	v_pk_add_f32 v[186:187], v[186:187], v[220:221]
	v_pk_add_f32 v[188:189], v[188:189], v[222:223]
	s_mov_b64 s[0:1], 0x1c01000
	v_lshl_add_u64 v[232:233], v[52:53], 0, s[0:1]
	global_load_dwordx4 v[208:211], v[232:233], off nt
	global_load_dwordx4 v[212:215], v[232:233], off offset:16 nt
	global_load_dwordx4 v[216:219], v[232:233], off offset:2048 nt
	global_load_dwordx4 v[220:223], v[232:233], off offset:2064 nt
	s_waitcnt vmcnt(8)
	v_pk_add_f32 v[174:175], v[174:175], v[224:225]
	v_pk_add_f32 v[176:177], v[176:177], v[226:227]
	v_pk_add_f32 v[178:179], v[178:179], v[228:229]
	v_pk_add_f32 v[180:181], v[180:181], v[230:231]
	v_pk_add_f32 v[182:183], v[182:183], v[238:239]
	v_pk_add_f32 v[184:185], v[184:185], v[240:241]
	v_pk_add_f32 v[186:187], v[186:187], v[242:243]
	v_pk_add_f32 v[188:189], v[188:189], v[244:245]
	s_mov_b64 s[0:1], 0x2001000
	v_lshl_add_u64 v[232:233], v[52:53], 0, s[0:1]
	global_load_dwordx4 v[224:227], v[232:233], off nt
	global_load_dwordx4 v[228:231], v[232:233], off offset:16 nt
	global_load_dwordx4 v[238:241], v[232:233], off offset:2048 nt
	global_load_dwordx4 v[242:245], v[232:233], off offset:2064 nt
	s_waitcnt vmcnt(8)
	v_pk_add_f32 v[174:175], v[174:175], v[190:191]
	v_pk_add_f32 v[176:177], v[176:177], v[192:193]
	v_pk_add_f32 v[178:179], v[178:179], v[194:195]
	v_pk_add_f32 v[180:181], v[180:181], v[196:197]
	v_pk_add_f32 v[182:183], v[182:183], v[198:199]
	v_pk_add_f32 v[184:185], v[184:185], v[200:201]
	v_pk_add_f32 v[186:187], v[186:187], v[204:205]
	v_pk_add_f32 v[188:189], v[188:189], v[206:207]
	s_mov_b64 s[0:1], 0x2401000
	v_lshl_add_u64 v[232:233], v[52:53], 0, s[0:1]
	global_load_dwordx4 v[190:193], v[232:233], off nt
	global_load_dwordx4 v[194:197], v[232:233], off offset:16 nt
	global_load_dwordx4 v[198:201], v[232:233], off offset:2048 nt
	global_load_dwordx4 v[204:207], v[232:233], off offset:2064 nt
	s_waitcnt vmcnt(8)
	v_pk_add_f32 v[174:175], v[174:175], v[208:209]
	v_pk_add_f32 v[176:177], v[176:177], v[210:211]
	v_pk_add_f32 v[178:179], v[178:179], v[212:213]
	v_pk_add_f32 v[180:181], v[180:181], v[214:215]
	v_pk_add_f32 v[182:183], v[182:183], v[216:217]
	v_pk_add_f32 v[184:185], v[184:185], v[218:219]
	v_pk_add_f32 v[186:187], v[186:187], v[220:221]
	v_pk_add_f32 v[188:189], v[188:189], v[222:223]
	s_mov_b64 s[0:1], 0x2801000
	v_lshl_add_u64 v[232:233], v[52:53], 0, s[0:1]
	global_load_dwordx4 v[208:211], v[232:233], off nt
	global_load_dwordx4 v[212:215], v[232:233], off offset:16 nt
	global_load_dwordx4 v[216:219], v[232:233], off offset:2048 nt
	global_load_dwordx4 v[220:223], v[232:233], off offset:2064 nt
	s_waitcnt vmcnt(8)
	v_pk_add_f32 v[174:175], v[174:175], v[224:225]
	v_pk_add_f32 v[176:177], v[176:177], v[226:227]
	v_pk_add_f32 v[178:179], v[178:179], v[228:229]
	v_pk_add_f32 v[180:181], v[180:181], v[230:231]
	v_pk_add_f32 v[182:183], v[182:183], v[238:239]
	v_pk_add_f32 v[184:185], v[184:185], v[240:241]
	v_pk_add_f32 v[186:187], v[186:187], v[242:243]
	v_pk_add_f32 v[188:189], v[188:189], v[244:245]
	global_load_dwordx4 v[224:227], v[76:77], off
	global_load_dwordx4 v[228:231], v[76:77], off offset:16
	global_load_dwordx4 v[238:241], v[78:79], off
	global_load_dwordx4 v[242:245], v[78:79], off offset:16
	s_waitcnt vmcnt(8)
	v_pk_add_f32 v[174:175], v[174:175], v[190:191]
	v_pk_add_f32 v[176:177], v[176:177], v[192:193]
	v_pk_add_f32 v[178:179], v[178:179], v[194:195]
	v_pk_add_f32 v[180:181], v[180:181], v[196:197]
	v_pk_add_f32 v[182:183], v[182:183], v[198:199]
	v_pk_add_f32 v[184:185], v[184:185], v[200:201]
	v_pk_add_f32 v[186:187], v[186:187], v[204:205]
	v_pk_add_f32 v[188:189], v[188:189], v[206:207]
	s_waitcnt vmcnt(4)
	v_pk_add_f32 v[174:175], v[174:175], v[208:209]
	v_pk_add_f32 v[176:177], v[176:177], v[210:211]
	v_pk_add_f32 v[178:179], v[178:179], v[212:213]
	v_pk_add_f32 v[180:181], v[180:181], v[214:215]
	v_pk_add_f32 v[182:183], v[182:183], v[216:217]
	v_pk_add_f32 v[184:185], v[184:185], v[218:219]
	v_pk_add_f32 v[186:187], v[186:187], v[220:221]
	v_pk_add_f32 v[188:189], v[188:189], v[222:223]
	s_waitcnt vmcnt(0)
	v_pk_fma_f32 v[60:61], v[174:175], v[224:225], v[60:61]
	v_pk_fma_f32 v[62:63], v[176:177], v[226:227], v[62:63]
	v_pk_fma_f32 v[58:59], v[178:179], v[228:229], v[58:59]
	v_pk_fma_f32 v[64:65], v[180:181], v[230:231], v[64:65]
	v_pk_fma_f32 v[54:55], v[182:183], v[238:239], v[54:55]
	v_pk_fma_f32 v[56:57], v[184:185], v[240:241], v[56:57]
	v_pk_fma_f32 v[32:33], v[186:187], v[242:243], v[32:33]
	v_pk_fma_f32 v[50:51], v[188:189], v[244:245], v[50:51]

.LBB0_1535:
	s_add_i32 s18, s10, s94
	s_cmp_lt_i32 s18, s95
	s_cselect_b64 s[16:17], -1, 0
	s_and_b64 s[0:1], s[16:17], exec
	s_waitcnt vmcnt(4)
	v_cvt_f32_f16_e32 v151, v47
	v_cvt_f32_f16_e32 v150, v46
	v_cvt_f32_f16_sdwa v153, v47 dst_sel:DWORD dst_unused:UNUSED_PAD src0_sel:WORD_1
	v_cvt_f32_f16_sdwa v152, v46 dst_sel:DWORD dst_unused:UNUSED_PAD src0_sel:WORD_1
	s_cselect_b32 s2, s18, s10
	s_ashr_i32 s3, s2, 31
	s_lshl_b64 s[14:15], s[2:3], 12
	v_cvt_f32_f16_e32 v159, v49
	v_cvt_f32_f16_e32 v158, v48
	v_lshl_add_u64 v[32:33], v[74:75], 0, s[14:15]
	v_pk_mul_f32 v[172:173], v[150:151], v[150:151]
	v_pk_mul_f32 v[174:175], v[152:153], v[152:153]
	v_cvt_f32_f16_sdwa v163, v49 dst_sel:DWORD dst_unused:UNUSED_PAD src0_sel:WORD_1
	v_cvt_f32_f16_sdwa v162, v48 dst_sel:DWORD dst_unused:UNUSED_PAD src0_sel:WORD_1
	global_load_dwordx4 v[62:65], v[32:33], off
	global_load_dwordx4 v[58:61], v[32:33], off offset:1024
	global_load_dwordx4 v[54:57], v[32:33], off offset:2048
	global_load_dwordx4 v[50:53], v[32:33], off offset:3072
	v_add_f32_e32 v33, v174, v172
	v_add_f32_e32 v33, v173, v33
	v_pk_mul_f32 v[176:177], v[158:159], v[158:159]
	v_cvt_f32_f16_e32 v47, v43
	v_cvt_f32_f16_e32 v46, v42
	v_add_f32_e32 v33, v175, v33
	v_pk_mul_f32 v[178:179], v[162:163], v[162:163]
	v_cvt_f32_f16_sdwa v49, v43 dst_sel:DWORD dst_unused:UNUSED_PAD src0_sel:WORD_1
	v_cvt_f32_f16_sdwa v48, v42 dst_sel:DWORD dst_unused:UNUSED_PAD src0_sel:WORD_1
	v_add_f32_e32 v33, v176, v33
	v_add_f32_e32 v33, v178, v33
	v_add_f32_e32 v33, v177, v33
	v_pk_mul_f32 v[180:181], v[46:47], v[46:47]
	v_cvt_f32_f16_e32 v157, v45
	v_cvt_f32_f16_e32 v156, v44
	v_add_f32_e32 v33, v179, v33
	v_pk_mul_f32 v[182:183], v[48:49], v[48:49]
	v_cvt_f32_f16_sdwa v161, v45 dst_sel:DWORD dst_unused:UNUSED_PAD src0_sel:WORD_1
	v_cvt_f32_f16_sdwa v160, v44 dst_sel:DWORD dst_unused:UNUSED_PAD src0_sel:WORD_1
	v_add_f32_e32 v33, v180, v33
	v_add_f32_e32 v33, v182, v33
	v_add_f32_e32 v33, v181, v33
	v_pk_mul_f32 v[184:185], v[156:157], v[156:157]
	v_cvt_f32_f16_e32 v43, v39
	v_cvt_f32_f16_e32 v42, v38
	v_add_f32_e32 v33, v183, v33
	v_pk_mul_f32 v[186:187], v[160:161], v[160:161]
	v_cvt_f32_f16_sdwa v45, v39 dst_sel:DWORD dst_unused:UNUSED_PAD src0_sel:WORD_1
	v_cvt_f32_f16_sdwa v44, v38 dst_sel:DWORD dst_unused:UNUSED_PAD src0_sel:WORD_1
	v_add_f32_e32 v33, v184, v33
	v_add_f32_e32 v33, v186, v33
	v_add_f32_e32 v33, v185, v33
	v_pk_mul_f32 v[188:189], v[42:43], v[42:43]
	v_cvt_f32_f16_e32 v155, v41
	v_cvt_f32_f16_e32 v154, v40
	v_add_f32_e32 v33, v187, v33
	v_pk_mul_f32 v[190:191], v[44:45], v[44:45]
	v_cvt_f32_f16_sdwa v41, v41 dst_sel:DWORD dst_unused:UNUSED_PAD src0_sel:WORD_1
	v_cvt_f32_f16_sdwa v40, v40 dst_sel:DWORD dst_unused:UNUSED_PAD src0_sel:WORD_1
	v_add_f32_e32 v33, v188, v33
	v_add_f32_e32 v33, v190, v33
	v_add_f32_e32 v33, v189, v33
	v_pk_mul_f32 v[192:193], v[154:155], v[154:155]
	v_cvt_f32_f16_e32 v39, v35
	v_cvt_f32_f16_e32 v38, v34
	v_add_f32_e32 v33, v191, v33
	v_pk_mul_f32 v[194:195], v[40:41], v[40:41]
	v_cvt_f32_f16_sdwa v35, v35 dst_sel:DWORD dst_unused:UNUSED_PAD src0_sel:WORD_1
	v_cvt_f32_f16_sdwa v34, v34 dst_sel:DWORD dst_unused:UNUSED_PAD src0_sel:WORD_1
	v_add_f32_e32 v33, v192, v33
	v_add_f32_e32 v33, v194, v33
	v_add_f32_e32 v33, v193, v33
	v_pk_mul_f32 v[196:197], v[38:39], v[38:39]
	v_add_f32_e32 v33, v195, v33
	v_pk_mul_f32 v[198:199], v[34:35], v[34:35]
	v_add_f32_e32 v33, v196, v33
	v_cvt_f32_f16_sdwa v149, v37 dst_sel:DWORD dst_unused:UNUSED_PAD src0_sel:WORD_1
	v_cvt_f32_f16_e32 v148, v37
	v_add_f32_e32 v33, v198, v33
	v_add_f32_e32 v33, v197, v33
	v_add_f32_e32 v33, v199, v33
	v_fma_mix_f32 v33, v36, v36, v33 op_sel_hi:[1,1,0]
	v_pk_mul_f32 v[170:171], v[148:149], v[148:149]
	v_fma_mix_f32 v33, v36, v36, v33 op_sel:[1,1,0] op_sel_hi:[1,1,0]
	v_cvt_f32_f16_e32 v144, v36
	v_add_f32_e32 v33, v170, v33
	v_add_f32_e32 v33, v171, v33
	v_cvt_f32_f16_sdwa v32, v36 dst_sel:DWORD dst_unused:UNUSED_PAD src0_sel:WORD_1
	ds_bpermute_b32 v36, v67, v33
	s_ashr_i32 s11, s10, 31
	s_lshl_b64 s[0:1], s[10:11], 12
	v_lshl_add_u64 v[146:147], v[76:77], 0, s[0:1]
	s_mov_b32 s0, 0xf800000
	s_waitcnt lgkmcnt(0)
	v_add_f32_e32 v33, v33, v36
	ds_bpermute_b32 v36, v164, v33
	s_waitcnt lgkmcnt(0)
	v_add_f32_e32 v33, v33, v36
	ds_bpermute_b32 v36, v165, v33
	s_waitcnt lgkmcnt(0)
	v_add_f32_e32 v33, v33, v36
	ds_bpermute_b32 v36, v166, v33
	s_waitcnt lgkmcnt(0)
	v_add_f32_e32 v33, v33, v36
	ds_bpermute_b32 v36, v167, v33
	s_waitcnt lgkmcnt(0)
	v_add_f32_e32 v33, v33, v36
	ds_bpermute_b32 v36, v168, v33
	s_waitcnt lgkmcnt(0)
	v_add_f32_e32 v33, v33, v36
	v_mov_b32_e32 v36, 0x358637bd
	v_fmamk_f32 v33, v33, 0x3a000000, v36
	v_cmp_gt_f32_e32 vcc, s0, v33
	v_mul_f32_e32 v36, 0x4f800000, v33
	s_nop 0
	v_cndmask_b32_e32 v33, v33, v36, vcc
	v_sqrt_f32_e32 v36, v33
	s_nop 0
	v_add_u32_e32 v37, -1, v36
	v_fma_f32 v145, -v37, v36, v33
	v_cmp_ge_f32_e64 s[8:9], 0, v145
	v_add_u32_e32 v145, 1, v36
	s_nop 0
	v_cndmask_b32_e64 v37, v36, v37, s[8:9]
	v_fma_f32 v36, -v145, v36, v33
	v_cmp_lt_f32_e64 s[8:9], 0, v36
	s_nop 1
	v_cndmask_b32_e64 v36, v37, v145, s[8:9]
	v_mul_f32_e32 v37, 0x37800000, v36
	v_cndmask_b32_e32 v36, v36, v37, vcc
	v_cmp_class_f32_e32 vcc, v33, v0
	s_nop 1
	v_cndmask_b32_e32 v33, v36, v33, vcc
	v_div_scale_f32 v36, s[0:1], v33, v33, 1.0
	v_rcp_f32_e32 v37, v36
	s_min_i32 s0, s2, 0x4000
	s_ashr_i32 s8, s0, 13
	s_cmp_eq_u32 s8, s19
	v_fma_f32 v145, -v36, v37, 1.0
	v_fmac_f32_e32 v37, v145, v37
	v_div_scale_f32 v145, vcc, 1.0, v33, 1.0
	v_mul_f32_e32 v169, v145, v37
	v_fma_f32 v170, -v36, v169, v145
	v_fmac_f32_e32 v169, v170, v37
	v_fma_f32 v36, -v36, v169, v145
	v_div_fmas_f32 v36, v36, v37, v169
	v_div_fixup_f32 v36, v36, v33, 1.0
	v_pk_mul_f32 v[152:153], v[36:37], v[152:153] op_sel_hi:[0,1]
	v_pk_mul_f32 v[162:163], v[36:37], v[162:163] op_sel_hi:[0,1]
	v_pk_mul_f32 v[150:151], v[36:37], v[150:151] op_sel_hi:[0,1]
	v_pk_fma_f32 v[152:153], v[80:81], v[152:153], v[142:143]
	v_pk_mul_f32 v[158:159], v[36:37], v[158:159] op_sel_hi:[0,1]
	v_pk_fma_f32 v[162:163], v[84:85], v[162:163], v[138:139]
	v_pk_fma_f32 v[150:151], v[78:79], v[150:151], v[140:141]
	v_pk_fma_f32 v[158:159], v[82:83], v[158:159], v[136:137]
	v_bfe_u32 v33, v163, 16, 1
	v_bfe_u32 v37, v162, 16, 1
	v_bfe_u32 v145, v153, 16, 1
	v_bfe_u32 v169, v152, 16, 1
	v_add3_u32 v169, v152, v169, s53
	v_add3_u32 v145, v153, v145, s53
	v_add3_u32 v37, v162, v37, s53
	v_add3_u32 v33, v163, v33, s53
	v_bfe_u32 v152, v150, 16, 1
	v_bfe_u32 v153, v151, 16, 1
	v_bfe_u32 v162, v158, 16, 1
	v_bfe_u32 v163, v159, 16, 1
	v_add3_u32 v159, v159, v163, s53
	v_add3_u32 v158, v158, v162, s53
	v_add3_u32 v151, v151, v153, s53
	v_add3_u32 v150, v150, v152, s53
	v_lshrrev_b32_e32 v150, 16, v150
	v_lshrrev_b32_e32 v151, 16, v151
	v_lshrrev_b32_e32 v152, 16, v158
	v_lshrrev_b32_e32 v153, 16, v159
	v_and_or_b32 v153, v33, s77, v153
	v_and_or_b32 v152, v37, s77, v152
	v_and_or_b32 v151, v145, s77, v151
	v_and_or_b32 v150, v169, s77, v150
	global_store_dwordx4 v[146:147], v[150:153], off
	v_pk_mul_f32 v[48:49], v[36:37], v[48:49] op_sel_hi:[0,1]
	v_pk_mul_f32 v[46:47], v[36:37], v[46:47] op_sel_hi:[0,1]
	v_pk_mul_f32 v[152:153], v[36:37], v[160:161] op_sel_hi:[0,1]
	v_pk_fma_f32 v[48:49], v[88:89], v[48:49], v[134:135]
	v_pk_mul_f32 v[150:151], v[36:37], v[156:157] op_sel_hi:[0,1]
	v_pk_fma_f32 v[152:153], v[92:93], v[152:153], v[130:131]
	v_pk_fma_f32 v[46:47], v[86:87], v[46:47], v[132:133]
	v_pk_fma_f32 v[150:151], v[90:91], v[150:151], v[128:129]
	v_bfe_u32 v33, v153, 16, 1
	v_bfe_u32 v37, v152, 16, 1
	v_bfe_u32 v145, v49, 16, 1
	v_bfe_u32 v156, v48, 16, 1
	v_add3_u32 v156, v48, v156, s53
	v_add3_u32 v145, v49, v145, s53
	v_add3_u32 v37, v152, v37, s53
	v_add3_u32 v33, v153, v33, s53
	v_bfe_u32 v48, v46, 16, 1
	v_bfe_u32 v49, v47, 16, 1
	v_bfe_u32 v152, v150, 16, 1
	v_bfe_u32 v153, v151, 16, 1
	v_add3_u32 v151, v151, v153, s53
	v_add3_u32 v150, v150, v152, s53
	v_add3_u32 v47, v47, v49, s53
	v_add3_u32 v46, v46, v48, s53
	v_lshrrev_b32_e32 v46, 16, v46
	v_lshrrev_b32_e32 v47, 16, v47
	v_lshrrev_b32_e32 v48, 16, v150
	v_lshrrev_b32_e32 v49, 16, v151
	v_and_or_b32 v49, v33, s77, v49
	v_and_or_b32 v48, v37, s77, v48
	v_and_or_b32 v47, v145, s77, v47
	v_and_or_b32 v46, v156, s77, v46
	v_pk_mul_f32 v[44:45], v[36:37], v[44:45] op_sel_hi:[0,1]
	global_store_dwordx4 v[146:147], v[46:49], off offset:1024
	v_pk_fma_f32 v[44:45], v[96:97], v[44:45], v[126:127]
	v_pk_mul_f32 v[40:41], v[36:37], v[40:41] op_sel_hi:[0,1]
	v_pk_mul_f32 v[46:47], v[36:37], v[154:155] op_sel_hi:[0,1]
	v_pk_mul_f32 v[42:43], v[36:37], v[42:43] op_sel_hi:[0,1]
	v_pk_fma_f32 v[46:47], v[98:99], v[46:47], v[120:121]
	v_pk_fma_f32 v[40:41], v[100:101], v[40:41], v[122:123]
	v_bfe_u32 v49, v44, 16, 1
	v_pk_fma_f32 v[42:43], v[94:95], v[42:43], v[124:125]
	v_bfe_u32 v33, v41, 16, 1
	v_bfe_u32 v37, v40, 16, 1
	v_bfe_u32 v48, v45, 16, 1
	v_add3_u32 v44, v44, v49, s53
	v_bfe_u32 v49, v47, 16, 1
	v_add3_u32 v45, v45, v48, s53
	v_add3_u32 v37, v40, v37, s53
	v_add3_u32 v33, v41, v33, s53
	v_bfe_u32 v40, v42, 16, 1
	v_bfe_u32 v41, v43, 16, 1
	v_bfe_u32 v48, v46, 16, 1
	v_add3_u32 v47, v47, v49, s53
	v_add3_u32 v46, v46, v48, s53
	v_add3_u32 v41, v43, v41, s53
	v_add3_u32 v40, v42, v40, s53
	v_lshrrev_b32_e32 v43, 16, v47
	v_lshrrev_b32_e32 v40, 16, v40
	v_lshrrev_b32_e32 v41, 16, v41
	v_lshrrev_b32_e32 v42, 16, v46
	v_and_or_b32 v43, v33, s77, v43
	v_mov_b32_e32 v33, v149
	v_and_or_b32 v42, v37, s77, v42
	v_and_or_b32 v41, v45, s77, v41
	v_and_or_b32 v40, v44, s77, v40
	v_pk_mul_f32 v[34:35], v[36:37], v[34:35] op_sel_hi:[0,1]
	v_mov_b32_e32 v145, v148
	v_pk_mul_f32 v[32:33], v[36:37], v[32:33] op_sel_hi:[0,1]
	global_store_dwordx4 v[146:147], v[40:43], off offset:2048
	v_pk_mul_f32 v[38:39], v[36:37], v[38:39] op_sel_hi:[0,1]
	v_pk_fma_f32 v[34:35], v[104:105], v[34:35], v[118:119]
	v_pk_mul_f32 v[40:41], v[36:37], v[144:145] op_sel_hi:[0,1]
	v_pk_fma_f32 v[32:33], v[108:109], v[32:33], v[114:115]
	v_pk_fma_f32 v[38:39], v[102:103], v[38:39], v[116:117]
	v_pk_fma_f32 v[40:41], v[106:107], v[40:41], v[112:113]
	v_bfe_u32 v36, v33, 16, 1
	v_bfe_u32 v37, v32, 16, 1
	v_bfe_u32 v42, v35, 16, 1
	v_bfe_u32 v43, v34, 16, 1
	v_add3_u32 v43, v34, v43, s53
	v_add3_u32 v42, v35, v42, s53
	v_add3_u32 v32, v32, v37, s53
	v_add3_u32 v33, v33, v36, s53
	v_bfe_u32 v34, v38, 16, 1
	v_bfe_u32 v35, v39, 16, 1
	v_bfe_u32 v36, v40, 16, 1
	v_bfe_u32 v37, v41, 16, 1
	v_add3_u32 v37, v41, v37, s53
	v_add3_u32 v36, v40, v36, s53
	v_add3_u32 v35, v39, v35, s53
	v_add3_u32 v34, v38, v34, s53
	v_lshrrev_b32_e32 v38, 16, v34
	v_lshrrev_b32_e32 v39, 16, v35
	v_lshrrev_b32_e32 v34, 16, v36
	v_lshrrev_b32_e32 v35, 16, v37
	v_and_or_b32 v35, v33, s77, v35
	v_and_or_b32 v34, v32, s77, v34
	v_and_or_b32 v33, v42, s77, v39
	v_and_or_b32 v32, v43, s77, v38
	global_store_dwordx4 v[146:147], v[32:35], off offset:3072
	s_cbranch_scc1 .LBB0_1537
	s_mul_i32 s1, s8, 0xc000
	s_mul_hi_i32 s0, s8, 0xc000
	s_add_u32 s2, s4, s1
	s_addc_u32 s3, s5, s0
	v_lshl_add_u64 v[44:45], s[2:3], 0, v[202:203]
	s_mov_b64 s[0:1], 0x2000
	v_lshl_add_u64 v[30:31], v[44:45], 0, s[0:1]
	s_movk_i32 s0, 0x3000
	v_add_co_u32_e32 v42, vcc, s0, v44
	global_load_dwordx4 v[10:13], v[68:69], off offset:16
	global_load_dwordx4 v[14:17], v[68:69], off
	global_load_dwordx4 v[2:5], v202, s[2:3]
	global_load_dwordx4 v[6:9], v202, s[2:3] offset:16
	v_addc_co_u32_e32 v43, vcc, 0, v45, vcc
	global_load_dwordx4 v[18:21], v[42:43], off offset:-4096
	global_load_dwordx4 v[22:25], v[30:31], off offset:16
	s_mov_b64 s[0:1], 0x1000
	s_mov_b32 s19, s8
	s_waitcnt vmcnt(3)
	v_mov_b32_e32 v140, v2
	s_waitcnt vmcnt(2)
	v_mov_b32_e32 v136, v6
	v_mov_b32_e32 v137, v8
	s_waitcnt vmcnt(1)
	v_mov_b32_e32 v27, v20
	v_mov_b32_e32 v20, v19
	v_mov_b32_e32 v26, v18
	v_pk_add_f32 v[18:19], v[20:21], 1.0 op_sel_hi:[1,0]
	v_mov_b32_e32 v20, v14
	v_mov_b32_e32 v21, v16
	v_mov_b32_e32 v16, v15
	s_waitcnt vmcnt(0)
	v_mov_b32_e32 v14, v22
	v_mov_b32_e32 v15, v24
	v_mov_b32_e32 v24, v23
	v_pk_add_f32 v[26:27], v[26:27], 1.0 op_sel_hi:[1,0]
	v_pk_mul_f32 v[80:81], v[16:17], v[18:19]
	v_pk_add_f32 v[14:15], v[14:15], 1.0 op_sel_hi:[1,0]
	v_pk_add_f32 v[16:17], v[24:25], 1.0 op_sel_hi:[1,0]
	v_mov_b32_e32 v18, v10
	v_mov_b32_e32 v19, v12
	v_mov_b32_e32 v12, v11
	v_pk_mul_f32 v[78:79], v[20:21], v[26:27]
	v_pk_mul_f32 v[82:83], v[18:19], v[14:15]
	v_pk_mul_f32 v[84:85], v[12:13], v[16:17]
	global_load_dwordx4 v[18:21], v[68:69], off offset:2064
	global_load_dwordx4 v[22:25], v[68:69], off offset:2048
	global_load_dwordx4 v[10:13], v202, s[2:3] offset:2048
	global_load_dwordx4 v[14:17], v202, s[2:3] offset:2064
	global_load_dwordx4 v[26:29], v[30:31], off offset:2064
	s_nop 0
	global_load_dwordx4 v[30:33], v[30:31], off offset:2048
	v_mov_b32_e32 v138, v7
	v_mov_b32_e32 v139, v9
	v_mov_b32_e32 v141, v4
	v_mov_b32_e32 v142, v3
	v_mov_b32_e32 v143, v5
	v_mov_b32_e32 v110, v3
	v_mov_b32_e32 v111, v5
	v_mov_b32_e32 v3, v4
	v_mov_b32_e32 v4, v7
	v_mov_b32_e32 v5, v9
	v_mov_b32_e32 v7, v8
	s_waitcnt vmcnt(3)
	v_mov_b32_e32 v132, v10
	s_waitcnt vmcnt(2)
	v_mov_b32_e32 v128, v14
	v_mov_b32_e32 v129, v16
	s_waitcnt vmcnt(0)
	v_mov_b32_e32 v35, v32
	v_mov_b32_e32 v32, v31
	v_mov_b32_e32 v34, v30
	v_pk_add_f32 v[30:31], v[32:33], 1.0 op_sel_hi:[1,0]
	v_mov_b32_e32 v32, v22
	v_mov_b32_e32 v33, v24
	v_mov_b32_e32 v24, v23
	v_mov_b32_e32 v22, v26
	v_mov_b32_e32 v23, v28
	v_pk_add_f32 v[22:23], v[22:23], 1.0 op_sel_hi:[1,0]
	v_mov_b32_e32 v28, v27
	v_mov_b32_e32 v26, v18
	v_mov_b32_e32 v27, v20
	v_pk_mul_f32 v[90:91], v[26:27], v[22:23]
	v_lshl_add_u64 v[22:23], v[44:45], 0, s[0:1]
	s_movk_i32 s0, 0x1000
	v_add_co_u32_e32 v46, vcc, s0, v44
	s_mov_b64 s[0:1], 0x3000
	v_pk_add_f32 v[34:35], v[34:35], 1.0 op_sel_hi:[1,0]
	v_pk_mul_f32 v[88:89], v[24:25], v[30:31]
	v_pk_add_f32 v[24:25], v[28:29], 1.0 op_sel_hi:[1,0]
	v_mov_b32_e32 v20, v19
	v_addc_co_u32_e32 v47, vcc, 0, v45, vcc
	v_lshl_add_u64 v[38:39], v[44:45], 0, s[0:1]
	v_pk_mul_f32 v[86:87], v[32:33], v[34:35]
	v_pk_mul_f32 v[92:93], v[20:21], v[24:25]
	global_load_dwordx4 v[26:29], v[70:71], off offset:16
	global_load_dwordx4 v[30:33], v[70:71], off
	global_load_dwordx4 v[18:21], v[46:47], off
	s_nop 0
	global_load_dwordx4 v[22:25], v[22:23], off offset:16
	s_nop 0
	global_load_dwordx4 v[34:37], v[42:43], off
	s_nop 0
	global_load_dwordx4 v[38:41], v[38:39], off offset:16
	s_mov_b64 s[0:1], 0x1800
	v_mov_b32_e32 v130, v15
	v_mov_b32_e32 v131, v17
	v_mov_b32_e32 v133, v12
	v_mov_b32_e32 v134, v11
	v_mov_b32_e32 v135, v13
	v_mov_b32_e32 v8, v11
	v_mov_b32_e32 v9, v13
	v_mov_b32_e32 v11, v12
	v_mov_b32_e32 v12, v15
	v_mov_b32_e32 v13, v17
	v_mov_b32_e32 v15, v16
	s_waitcnt vmcnt(3)
	v_mov_b32_e32 v124, v18
	s_waitcnt vmcnt(1)
	v_mov_b32_e32 v49, v36
	v_mov_b32_e32 v36, v35
	v_mov_b32_e32 v48, v34
	v_pk_add_f32 v[34:35], v[36:37], 1.0 op_sel_hi:[1,0]
	v_mov_b32_e32 v36, v30
	v_mov_b32_e32 v37, v32
	v_mov_b32_e32 v32, v31
	s_waitcnt vmcnt(0)
	v_mov_b32_e32 v30, v38
	v_mov_b32_e32 v31, v40
	v_pk_mul_f32 v[96:97], v[32:33], v[34:35]
	v_pk_add_f32 v[30:31], v[30:31], 1.0 op_sel_hi:[1,0]
	v_mov_b32_e32 v40, v39
	v_mov_b32_e32 v34, v26
	v_mov_b32_e32 v35, v28
	v_pk_add_f32 v[48:49], v[48:49], 1.0 op_sel_hi:[1,0]
	v_pk_add_f32 v[32:33], v[40:41], 1.0 op_sel_hi:[1,0]
	v_pk_mul_f32 v[98:99], v[34:35], v[30:31]
	v_mov_b32_e32 v28, v27
	v_lshl_add_u64 v[30:31], v[44:45], 0, s[0:1]
	s_mov_b64 s[0:1], 0x3800
	v_pk_mul_f32 v[94:95], v[36:37], v[48:49]
	v_pk_mul_f32 v[100:101], v[28:29], v[32:33]
	global_load_dwordx4 v[34:37], v[72:73], off offset:16
	global_load_dwordx4 v[38:41], v[72:73], off
	global_load_dwordx4 v[26:29], v[46:47], off offset:2048
	s_nop 0
	global_load_dwordx4 v[30:33], v[30:31], off offset:16
	v_lshl_add_u64 v[46:47], v[44:45], 0, s[0:1]
	global_load_dwordx4 v[42:45], v[42:43], off offset:2048
	s_nop 0
	global_load_dwordx4 v[46:49], v[46:47], off offset:16
	v_mov_b32_e32 v120, v22
	v_mov_b32_e32 v121, v24
	v_mov_b32_e32 v122, v23
	v_mov_b32_e32 v123, v25
	v_mov_b32_e32 v125, v20
	v_mov_b32_e32 v126, v19
	v_mov_b32_e32 v127, v21
	v_mov_b32_e32 v16, v19
	v_mov_b32_e32 v17, v21
	v_mov_b32_e32 v19, v20
	v_mov_b32_e32 v20, v23
	v_mov_b32_e32 v21, v25
	v_mov_b32_e32 v23, v24
	s_waitcnt vmcnt(3)
	v_mov_b32_e32 v116, v26
	s_waitcnt vmcnt(2)
	v_mov_b32_e32 v112, v30
	s_waitcnt vmcnt(1)
	v_mov_b32_e32 v103, v44
	v_mov_b32_e32 v44, v43
	v_mov_b32_e32 v102, v42
	v_pk_add_f32 v[42:43], v[44:45], 1.0 op_sel_hi:[1,0]
	v_mov_b32_e32 v44, v38
	v_mov_b32_e32 v45, v40
	v_mov_b32_e32 v40, v39
	s_waitcnt vmcnt(0)
	v_mov_b32_e32 v38, v46
	v_mov_b32_e32 v39, v48
	v_mov_b32_e32 v48, v47
	v_pk_add_f32 v[102:103], v[102:103], 1.0 op_sel_hi:[1,0]
	v_pk_mul_f32 v[104:105], v[40:41], v[42:43]
	v_pk_add_f32 v[38:39], v[38:39], 1.0 op_sel_hi:[1,0]
	v_pk_add_f32 v[40:41], v[48:49], 1.0 op_sel_hi:[1,0]
	v_mov_b32_e32 v42, v34
	v_mov_b32_e32 v43, v36
	v_mov_b32_e32 v36, v35
	v_pk_mul_f32 v[102:103], v[44:45], v[102:103]
	v_pk_mul_f32 v[106:107], v[42:43], v[38:39]
	v_pk_mul_f32 v[108:109], v[36:37], v[40:41]
	v_mov_b32_e32 v113, v32
	v_mov_b32_e32 v114, v31
	v_mov_b32_e32 v115, v33
	v_mov_b32_e32 v117, v28
	v_mov_b32_e32 v118, v27
	v_mov_b32_e32 v119, v29
	v_mov_b32_e32 v24, v27
	v_mov_b32_e32 v25, v29
	v_mov_b32_e32 v27, v28
	v_mov_b32_e32 v28, v31
	v_mov_b32_e32 v29, v33
	v_mov_b32_e32 v31, v32

.LBB0_1806:
	s_add_i32 s14, s4, s94
	s_cmpk_lt_i32 s14, 0x4200
	s_cselect_b64 s[8:9], -1, 0
	s_and_b64 s[0:1], s[8:9], exec
	s_cselect_b32 s6, s14, s4
	s_ashr_i32 s7, s6, 31
	s_lshl_b64 s[0:1], s[6:7], 12
	v_lshl_add_u64 v[32:33], v[80:81], 0, s[0:1]
	s_waitcnt vmcnt(4)
	global_load_dwordx4 v[62:65], v[32:33], off
	global_load_dwordx4 v[58:61], v[32:33], off offset:1024
	global_load_dwordx4 v[54:57], v[32:33], off offset:2048
	global_load_dwordx4 v[50:53], v[32:33], off offset:3072
	v_cvt_f32_f16_sdwa v167, v46 dst_sel:DWORD dst_unused:UNUSED_PAD src0_sel:WORD_1
	v_cvt_f32_f16_e32 v166, v46
	v_cvt_f32_f16_sdwa v163, v47 dst_sel:DWORD dst_unused:UNUSED_PAD src0_sel:WORD_1
	v_cvt_f32_f16_e32 v162, v47
	v_cvt_f32_f16_sdwa v161, v48 dst_sel:DWORD dst_unused:UNUSED_PAD src0_sel:WORD_1
	v_cvt_f32_f16_e32 v160, v48
	v_cvt_f32_f16_sdwa v165, v49 dst_sel:DWORD dst_unused:UNUSED_PAD src0_sel:WORD_1
	v_cvt_f32_f16_e32 v164, v49
	v_cvt_f32_f16_sdwa v155, v42 dst_sel:DWORD dst_unused:UNUSED_PAD src0_sel:WORD_1
	v_cvt_f32_f16_e32 v154, v42
	v_cvt_f32_f16_sdwa v157, v43 dst_sel:DWORD dst_unused:UNUSED_PAD src0_sel:WORD_1
	v_cvt_f32_f16_e32 v156, v43
	v_cvt_f32_f16_sdwa v153, v44 dst_sel:DWORD dst_unused:UNUSED_PAD src0_sel:WORD_1
	v_cvt_f32_f16_e32 v152, v44
	v_cvt_f32_f16_sdwa v159, v45 dst_sel:DWORD dst_unused:UNUSED_PAD src0_sel:WORD_1
	v_cvt_f32_f16_e32 v158, v45
	v_cvt_f32_f16_sdwa v45, v38 dst_sel:DWORD dst_unused:UNUSED_PAD src0_sel:WORD_1
	v_cvt_f32_f16_e32 v44, v38
	v_cvt_f32_f16_sdwa v47, v39 dst_sel:DWORD dst_unused:UNUSED_PAD src0_sel:WORD_1
	v_cvt_f32_f16_e32 v46, v39
	v_cvt_f32_f16_sdwa v43, v40 dst_sel:DWORD dst_unused:UNUSED_PAD src0_sel:WORD_1
	v_cvt_f32_f16_e32 v42, v40
	v_cvt_f32_f16_sdwa v49, v41 dst_sel:DWORD dst_unused:UNUSED_PAD src0_sel:WORD_1
	v_cvt_f32_f16_e32 v48, v41
	v_cvt_f32_f16_sdwa v39, v34 dst_sel:DWORD dst_unused:UNUSED_PAD src0_sel:WORD_1
	v_cvt_f32_f16_e32 v38, v34
	v_cvt_f32_f16_sdwa v41, v35 dst_sel:DWORD dst_unused:UNUSED_PAD src0_sel:WORD_1
	v_cvt_f32_f16_e32 v40, v35
	v_cvt_f32_f16_sdwa v33, v36 dst_sel:DWORD dst_unused:UNUSED_PAD src0_sel:WORD_1
	v_cvt_f32_f16_e32 v32, v36
	v_cvt_f32_f16_sdwa v35, v37 dst_sel:DWORD dst_unused:UNUSED_PAD src0_sel:WORD_1
	v_cvt_f32_f16_e32 v34, v37
	s_cmpk_gt_i32 s4, 0x3fff
	s_cselect_b64 s[2:3], -1, 0
	s_cmpk_lt_i32 s4, 0x4000
	s_cbranch_scc1 .LBB0_1808
	s_add_i32 s86, s4, 0xffffc000
	s_lshl_b64 s[0:1], s[86:87], 13
	v_lshl_add_u64 v[36:37], v[82:83], 0, s[0:1]
	global_load_dwordx4 v[190:193], v[36:37], off nt
	global_load_dwordx4 v[194:197], v[36:37], off offset:16 nt
	global_load_dwordx4 v[198:201], v[36:37], off offset:2048 nt
	global_load_dwordx4 v[204:207], v[36:37], off offset:2064 nt
	s_mov_b64 s[0:1], 0x400000
	v_lshl_add_u64 v[232:233], v[36:37], 0, s[0:1]
	global_load_dwordx4 v[208:211], v[232:233], off nt
	global_load_dwordx4 v[212:215], v[232:233], off offset:16 nt
	global_load_dwordx4 v[216:219], v[232:233], off offset:2048 nt
	global_load_dwordx4 v[220:223], v[232:233], off offset:2064 nt
	s_mov_b64 s[0:1], 0x800000
	v_lshl_add_u64 v[232:233], v[36:37], 0, s[0:1]
	global_load_dwordx4 v[224:227], v[232:233], off nt
	global_load_dwordx4 v[228:231], v[232:233], off offset:16 nt
	global_load_dwordx4 v[238:241], v[232:233], off offset:2048 nt
	global_load_dwordx4 v[242:245], v[232:233], off offset:2064 nt
	s_waitcnt vmcnt(8)
	v_mov_b64_e32 v[174:175], v[190:191]
	v_mov_b64_e32 v[176:177], v[192:193]
	v_mov_b64_e32 v[178:179], v[194:195]
	v_mov_b64_e32 v[180:181], v[196:197]
	v_mov_b64_e32 v[182:183], v[198:199]
	v_mov_b64_e32 v[184:185], v[200:201]
	v_mov_b64_e32 v[186:187], v[204:205]
	v_mov_b64_e32 v[188:189], v[206:207]
	s_mov_b64 s[0:1], 0xc00000
	v_lshl_add_u64 v[232:233], v[36:37], 0, s[0:1]
	global_load_dwordx4 v[190:193], v[232:233], off nt
	global_load_dwordx4 v[194:197], v[232:233], off offset:16 nt
	global_load_dwordx4 v[198:201], v[232:233], off offset:2048 nt
	global_load_dwordx4 v[204:207], v[232:233], off offset:2064 nt
	s_waitcnt vmcnt(8)
	v_pk_add_f32 v[174:175], v[174:175], v[208:209]
	v_pk_add_f32 v[176:177], v[176:177], v[210:211]
	v_pk_add_f32 v[178:179], v[178:179], v[212:213]
	v_pk_add_f32 v[180:181], v[180:181], v[214:215]
	v_pk_add_f32 v[182:183], v[182:183], v[216:217]
	v_pk_add_f32 v[184:185], v[184:185], v[218:219]
	v_pk_add_f32 v[186:187], v[186:187], v[220:221]
	v_pk_add_f32 v[188:189], v[188:189], v[222:223]
	s_mov_b64 s[0:1], 0x1000000
	v_lshl_add_u64 v[232:233], v[36:37], 0, s[0:1]
	global_load_dwordx4 v[208:211], v[232:233], off nt
	global_load_dwordx4 v[212:215], v[232:233], off offset:16 nt
	global_load_dwordx4 v[216:219], v[232:233], off offset:2048 nt
	global_load_dwordx4 v[220:223], v[232:233], off offset:2064 nt
	s_waitcnt vmcnt(8)
	v_pk_add_f32 v[174:175], v[174:175], v[224:225]
	v_pk_add_f32 v[176:177], v[176:177], v[226:227]
	v_pk_add_f32 v[178:179], v[178:179], v[228:229]
	v_pk_add_f32 v[180:181], v[180:181], v[230:231]
	v_pk_add_f32 v[182:183], v[182:183], v[238:239]
	v_pk_add_f32 v[184:185], v[184:185], v[240:241]
	v_pk_add_f32 v[186:187], v[186:187], v[242:243]
	v_pk_add_f32 v[188:189], v[188:189], v[244:245]
	s_mov_b64 s[0:1], 0x1400000
	v_lshl_add_u64 v[232:233], v[36:37], 0, s[0:1]
	global_load_dwordx4 v[224:227], v[232:233], off nt
	global_load_dwordx4 v[228:231], v[232:233], off offset:16 nt
	global_load_dwordx4 v[238:241], v[232:233], off offset:2048 nt
	global_load_dwordx4 v[242:245], v[232:233], off offset:2064 nt
	s_waitcnt vmcnt(8)
	v_pk_add_f32 v[174:175], v[174:175], v[190:191]
	v_pk_add_f32 v[176:177], v[176:177], v[192:193]
	v_pk_add_f32 v[178:179], v[178:179], v[194:195]
	v_pk_add_f32 v[180:181], v[180:181], v[196:197]
	v_pk_add_f32 v[182:183], v[182:183], v[198:199]
	v_pk_add_f32 v[184:185], v[184:185], v[200:201]
	v_pk_add_f32 v[186:187], v[186:187], v[204:205]
	v_pk_add_f32 v[188:189], v[188:189], v[206:207]
	s_mov_b64 s[0:1], 0x1800000
	v_lshl_add_u64 v[232:233], v[36:37], 0, s[0:1]
	global_load_dwordx4 v[190:193], v[232:233], off nt
	global_load_dwordx4 v[194:197], v[232:233], off offset:16 nt
	global_load_dwordx4 v[198:201], v[232:233], off offset:2048 nt
	global_load_dwordx4 v[204:207], v[232:233], off offset:2064 nt
	s_waitcnt vmcnt(8)
	v_pk_add_f32 v[174:175], v[174:175], v[208:209]
	v_pk_add_f32 v[176:177], v[176:177], v[210:211]
	v_pk_add_f32 v[178:179], v[178:179], v[212:213]
	v_pk_add_f32 v[180:181], v[180:181], v[214:215]
	v_pk_add_f32 v[182:183], v[182:183], v[216:217]
	v_pk_add_f32 v[184:185], v[184:185], v[218:219]
	v_pk_add_f32 v[186:187], v[186:187], v[220:221]
	v_pk_add_f32 v[188:189], v[188:189], v[222:223]
	s_mov_b64 s[0:1], 0x1c00000
	v_lshl_add_u64 v[232:233], v[36:37], 0, s[0:1]
	global_load_dwordx4 v[208:211], v[232:233], off nt
	global_load_dwordx4 v[212:215], v[232:233], off offset:16 nt
	global_load_dwordx4 v[216:219], v[232:233], off offset:2048 nt
	global_load_dwordx4 v[220:223], v[232:233], off offset:2064 nt
	s_waitcnt vmcnt(8)
	v_pk_add_f32 v[174:175], v[174:175], v[224:225]
	v_pk_add_f32 v[176:177], v[176:177], v[226:227]
	v_pk_add_f32 v[178:179], v[178:179], v[228:229]
	v_pk_add_f32 v[180:181], v[180:181], v[230:231]
	v_pk_add_f32 v[182:183], v[182:183], v[238:239]
	v_pk_add_f32 v[184:185], v[184:185], v[240:241]
	v_pk_add_f32 v[186:187], v[186:187], v[242:243]
	v_pk_add_f32 v[188:189], v[188:189], v[244:245]
	s_mov_b64 s[0:1], 0x2000000
	v_lshl_add_u64 v[232:233], v[36:37], 0, s[0:1]
	global_load_dwordx4 v[224:227], v[232:233], off nt
	global_load_dwordx4 v[228:231], v[232:233], off offset:16 nt
	global_load_dwordx4 v[238:241], v[232:233], off offset:2048 nt
	global_load_dwordx4 v[242:245], v[232:233], off offset:2064 nt
	s_waitcnt vmcnt(8)
	v_pk_add_f32 v[174:175], v[174:175], v[190:191]
	v_pk_add_f32 v[176:177], v[176:177], v[192:193]
	v_pk_add_f32 v[178:179], v[178:179], v[194:195]
	v_pk_add_f32 v[180:181], v[180:181], v[196:197]
	v_pk_add_f32 v[182:183], v[182:183], v[198:199]
	v_pk_add_f32 v[184:185], v[184:185], v[200:201]
	v_pk_add_f32 v[186:187], v[186:187], v[204:205]
	v_pk_add_f32 v[188:189], v[188:189], v[206:207]
	s_mov_b64 s[0:1], 0x2400000
	v_lshl_add_u64 v[232:233], v[36:37], 0, s[0:1]
	global_load_dwordx4 v[190:193], v[232:233], off nt
	global_load_dwordx4 v[194:197], v[232:233], off offset:16 nt
	global_load_dwordx4 v[198:201], v[232:233], off offset:2048 nt
	global_load_dwordx4 v[204:207], v[232:233], off offset:2064 nt
	s_waitcnt vmcnt(8)
	v_pk_add_f32 v[174:175], v[174:175], v[208:209]
	v_pk_add_f32 v[176:177], v[176:177], v[210:211]
	v_pk_add_f32 v[178:179], v[178:179], v[212:213]
	v_pk_add_f32 v[180:181], v[180:181], v[214:215]
	v_pk_add_f32 v[182:183], v[182:183], v[216:217]
	v_pk_add_f32 v[184:185], v[184:185], v[218:219]
	v_pk_add_f32 v[186:187], v[186:187], v[220:221]
	v_pk_add_f32 v[188:189], v[188:189], v[222:223]
	s_mov_b64 s[0:1], 0x2800000
	v_lshl_add_u64 v[232:233], v[36:37], 0, s[0:1]
	global_load_dwordx4 v[208:211], v[232:233], off nt
	global_load_dwordx4 v[212:215], v[232:233], off offset:16 nt
	global_load_dwordx4 v[216:219], v[232:233], off offset:2048 nt
	global_load_dwordx4 v[220:223], v[232:233], off offset:2064 nt
	s_waitcnt vmcnt(8)
	v_pk_add_f32 v[174:175], v[174:175], v[224:225]
	v_pk_add_f32 v[176:177], v[176:177], v[226:227]
	v_pk_add_f32 v[178:179], v[178:179], v[228:229]
	v_pk_add_f32 v[180:181], v[180:181], v[230:231]
	v_pk_add_f32 v[182:183], v[182:183], v[238:239]
	v_pk_add_f32 v[184:185], v[184:185], v[240:241]
	v_pk_add_f32 v[186:187], v[186:187], v[242:243]
	v_pk_add_f32 v[188:189], v[188:189], v[244:245]
	global_load_dwordx4 v[224:227], v[74:75], off
	global_load_dwordx4 v[228:231], v[74:75], off offset:16
	global_load_dwordx4 v[238:241], v[74:75], off offset:2048
	global_load_dwordx4 v[242:245], v[74:75], off offset:2064
	s_waitcnt vmcnt(8)
	v_pk_add_f32 v[174:175], v[174:175], v[190:191]
	v_pk_add_f32 v[176:177], v[176:177], v[192:193]
	v_pk_add_f32 v[178:179], v[178:179], v[194:195]
	v_pk_add_f32 v[180:181], v[180:181], v[196:197]
	v_pk_add_f32 v[182:183], v[182:183], v[198:199]
	v_pk_add_f32 v[184:185], v[184:185], v[200:201]
	v_pk_add_f32 v[186:187], v[186:187], v[204:205]
	v_pk_add_f32 v[188:189], v[188:189], v[206:207]
	s_mov_b64 s[0:1], 0x1000
	v_lshl_add_u64 v[232:233], v[36:37], 0, s[0:1]
	global_load_dwordx4 v[190:193], v[232:233], off nt
	global_load_dwordx4 v[194:197], v[232:233], off offset:16 nt
	global_load_dwordx4 v[198:201], v[232:233], off offset:2048 nt
	global_load_dwordx4 v[204:207], v[232:233], off offset:2064 nt
	s_waitcnt vmcnt(8)
	v_pk_add_f32 v[174:175], v[174:175], v[208:209]
	v_pk_add_f32 v[176:177], v[176:177], v[210:211]
	v_pk_add_f32 v[178:179], v[178:179], v[212:213]
	v_pk_add_f32 v[180:181], v[180:181], v[214:215]
	v_pk_add_f32 v[182:183], v[182:183], v[216:217]
	v_pk_add_f32 v[184:185], v[184:185], v[218:219]
	v_pk_add_f32 v[186:187], v[186:187], v[220:221]
	v_pk_add_f32 v[188:189], v[188:189], v[222:223]
	s_mov_b64 s[0:1], 0x401000
	v_lshl_add_u64 v[232:233], v[36:37], 0, s[0:1]
	global_load_dwordx4 v[208:211], v[232:233], off nt
	global_load_dwordx4 v[212:215], v[232:233], off offset:16 nt
	global_load_dwordx4 v[216:219], v[232:233], off offset:2048 nt
	global_load_dwordx4 v[220:223], v[232:233], off offset:2064 nt
	s_waitcnt vmcnt(8)
	v_pk_fma_f32 v[166:167], v[174:175], v[224:225], v[166:167]
	v_pk_fma_f32 v[162:163], v[176:177], v[226:227], v[162:163]
	v_pk_fma_f32 v[160:161], v[178:179], v[228:229], v[160:161]
	v_pk_fma_f32 v[164:165], v[180:181], v[230:231], v[164:165]
	v_pk_fma_f32 v[154:155], v[182:183], v[238:239], v[154:155]
	v_pk_fma_f32 v[156:157], v[184:185], v[240:241], v[156:157]
	v_pk_fma_f32 v[152:153], v[186:187], v[242:243], v[152:153]
	v_pk_fma_f32 v[158:159], v[188:189], v[244:245], v[158:159]
	s_mov_b64 s[0:1], 0x801000
	v_lshl_add_u64 v[232:233], v[36:37], 0, s[0:1]
	global_load_dwordx4 v[224:227], v[232:233], off nt
	global_load_dwordx4 v[228:231], v[232:233], off offset:16 nt
	global_load_dwordx4 v[238:241], v[232:233], off offset:2048 nt
	global_load_dwordx4 v[242:245], v[232:233], off offset:2064 nt
	s_waitcnt vmcnt(8)
	v_mov_b64_e32 v[174:175], v[190:191]
	v_mov_b64_e32 v[176:177], v[192:193]
	v_mov_b64_e32 v[178:179], v[194:195]
	v_mov_b64_e32 v[180:181], v[196:197]
	v_mov_b64_e32 v[182:183], v[198:199]
	v_mov_b64_e32 v[184:185], v[200:201]
	v_mov_b64_e32 v[186:187], v[204:205]
	v_mov_b64_e32 v[188:189], v[206:207]
	s_mov_b64 s[0:1], 0xc01000
	v_lshl_add_u64 v[232:233], v[36:37], 0, s[0:1]
	global_load_dwordx4 v[190:193], v[232:233], off nt
	global_load_dwordx4 v[194:197], v[232:233], off offset:16 nt
	global_load_dwordx4 v[198:201], v[232:233], off offset:2048 nt
	global_load_dwordx4 v[204:207], v[232:233], off offset:2064 nt
	s_waitcnt vmcnt(8)
	v_pk_add_f32 v[174:175], v[174:175], v[208:209]
	v_pk_add_f32 v[176:177], v[176:177], v[210:211]
	v_pk_add_f32 v[178:179], v[178:179], v[212:213]
	v_pk_add_f32 v[180:181], v[180:181], v[214:215]
	v_pk_add_f32 v[182:183], v[182:183], v[216:217]
	v_pk_add_f32 v[184:185], v[184:185], v[218:219]
	v_pk_add_f32 v[186:187], v[186:187], v[220:221]
	v_pk_add_f32 v[188:189], v[188:189], v[222:223]
	s_mov_b64 s[0:1], 0x1001000
	v_lshl_add_u64 v[232:233], v[36:37], 0, s[0:1]
	global_load_dwordx4 v[208:211], v[232:233], off nt
	global_load_dwordx4 v[212:215], v[232:233], off offset:16 nt
	global_load_dwordx4 v[216:219], v[232:233], off offset:2048 nt
	global_load_dwordx4 v[220:223], v[232:233], off offset:2064 nt
	s_waitcnt vmcnt(8)
	v_pk_add_f32 v[174:175], v[174:175], v[224:225]
	v_pk_add_f32 v[176:177], v[176:177], v[226:227]
	v_pk_add_f32 v[178:179], v[178:179], v[228:229]
	v_pk_add_f32 v[180:181], v[180:181], v[230:231]
	v_pk_add_f32 v[182:183], v[182:183], v[238:239]
	v_pk_add_f32 v[184:185], v[184:185], v[240:241]
	v_pk_add_f32 v[186:187], v[186:187], v[242:243]
	v_pk_add_f32 v[188:189], v[188:189], v[244:245]
	s_mov_b64 s[0:1], 0x1401000
	v_lshl_add_u64 v[232:233], v[36:37], 0, s[0:1]
	global_load_dwordx4 v[224:227], v[232:233], off nt
	global_load_dwordx4 v[228:231], v[232:233], off offset:16 nt
	global_load_dwordx4 v[238:241], v[232:233], off offset:2048 nt
	global_load_dwordx4 v[242:245], v[232:233], off offset:2064 nt
	s_waitcnt vmcnt(8)
	v_pk_add_f32 v[174:175], v[174:175], v[190:191]
	v_pk_add_f32 v[176:177], v[176:177], v[192:193]
	v_pk_add_f32 v[178:179], v[178:179], v[194:195]
	v_pk_add_f32 v[180:181], v[180:181], v[196:197]
	v_pk_add_f32 v[182:183], v[182:183], v[198:199]
	v_pk_add_f32 v[184:185], v[184:185], v[200:201]
	v_pk_add_f32 v[186:187], v[186:187], v[204:205]
	v_pk_add_f32 v[188:189], v[188:189], v[206:207]
	s_mov_b64 s[0:1], 0x1801000
	v_lshl_add_u64 v[232:233], v[36:37], 0, s[0:1]
	global_load_dwordx4 v[190:193], v[232:233], off nt
	global_load_dwordx4 v[194:197], v[232:233], off offset:16 nt
	global_load_dwordx4 v[198:201], v[232:233], off offset:2048 nt
	global_load_dwordx4 v[204:207], v[232:233], off offset:2064 nt
	s_waitcnt vmcnt(8)
	v_pk_add_f32 v[174:175], v[174:175], v[208:209]
	v_pk_add_f32 v[176:177], v[176:177], v[210:211]
	v_pk_add_f32 v[178:179], v[178:179], v[212:213]
	v_pk_add_f32 v[180:181], v[180:181], v[214:215]
	v_pk_add_f32 v[182:183], v[182:183], v[216:217]
	v_pk_add_f32 v[184:185], v[184:185], v[218:219]
	v_pk_add_f32 v[186:187], v[186:187], v[220:221]
	v_pk_add_f32 v[188:189], v[188:189], v[222:223]
	s_mov_b64 s[0:1], 0x1c01000
	v_lshl_add_u64 v[232:233], v[36:37], 0, s[0:1]
	global_load_dwordx4 v[208:211], v[232:233], off nt
	global_load_dwordx4 v[212:215], v[232:233], off offset:16 nt
	global_load_dwordx4 v[216:219], v[232:233], off offset:2048 nt
	global_load_dwordx4 v[220:223], v[232:233], off offset:2064 nt
	s_waitcnt vmcnt(8)
	v_pk_add_f32 v[174:175], v[174:175], v[224:225]
	v_pk_add_f32 v[176:177], v[176:177], v[226:227]
	v_pk_add_f32 v[178:179], v[178:179], v[228:229]
	v_pk_add_f32 v[180:181], v[180:181], v[230:231]
	v_pk_add_f32 v[182:183], v[182:183], v[238:239]
	v_pk_add_f32 v[184:185], v[184:185], v[240:241]
	v_pk_add_f32 v[186:187], v[186:187], v[242:243]
	v_pk_add_f32 v[188:189], v[188:189], v[244:245]
	s_mov_b64 s[0:1], 0x2001000
	v_lshl_add_u64 v[232:233], v[36:37], 0, s[0:1]
	global_load_dwordx4 v[224:227], v[232:233], off nt
	global_load_dwordx4 v[228:231], v[232:233], off offset:16 nt
	global_load_dwordx4 v[238:241], v[232:233], off offset:2048 nt
	global_load_dwordx4 v[242:245], v[232:233], off offset:2064 nt
	s_waitcnt vmcnt(8)
	v_pk_add_f32 v[174:175], v[174:175], v[190:191]
	v_pk_add_f32 v[176:177], v[176:177], v[192:193]
	v_pk_add_f32 v[178:179], v[178:179], v[194:195]
	v_pk_add_f32 v[180:181], v[180:181], v[196:197]
	v_pk_add_f32 v[182:183], v[182:183], v[198:199]
	v_pk_add_f32 v[184:185], v[184:185], v[200:201]
	v_pk_add_f32 v[186:187], v[186:187], v[204:205]
	v_pk_add_f32 v[188:189], v[188:189], v[206:207]
	s_mov_b64 s[0:1], 0x2401000
	v_lshl_add_u64 v[232:233], v[36:37], 0, s[0:1]
	global_load_dwordx4 v[190:193], v[232:233], off nt
	global_load_dwordx4 v[194:197], v[232:233], off offset:16 nt
	global_load_dwordx4 v[198:201], v[232:233], off offset:2048 nt
	global_load_dwordx4 v[204:207], v[232:233], off offset:2064 nt
	s_waitcnt vmcnt(8)
	v_pk_add_f32 v[174:175], v[174:175], v[208:209]
	v_pk_add_f32 v[176:177], v[176:177], v[210:211]
	v_pk_add_f32 v[178:179], v[178:179], v[212:213]
	v_pk_add_f32 v[180:181], v[180:181], v[214:215]
	v_pk_add_f32 v[182:183], v[182:183], v[216:217]
	v_pk_add_f32 v[184:185], v[184:185], v[218:219]
	v_pk_add_f32 v[186:187], v[186:187], v[220:221]
	v_pk_add_f32 v[188:189], v[188:189], v[222:223]
	s_mov_b64 s[0:1], 0x2801000
	v_lshl_add_u64 v[232:233], v[36:37], 0, s[0:1]
	global_load_dwordx4 v[208:211], v[232:233], off nt
	global_load_dwordx4 v[212:215], v[232:233], off offset:16 nt
	global_load_dwordx4 v[216:219], v[232:233], off offset:2048 nt
	global_load_dwordx4 v[220:223], v[232:233], off offset:2064 nt
	s_waitcnt vmcnt(8)
	v_pk_add_f32 v[174:175], v[174:175], v[224:225]
	v_pk_add_f32 v[176:177], v[176:177], v[226:227]
	v_pk_add_f32 v[178:179], v[178:179], v[228:229]
	v_pk_add_f32 v[180:181], v[180:181], v[230:231]
	v_pk_add_f32 v[182:183], v[182:183], v[238:239]
	v_pk_add_f32 v[184:185], v[184:185], v[240:241]
	v_pk_add_f32 v[186:187], v[186:187], v[242:243]
	v_pk_add_f32 v[188:189], v[188:189], v[244:245]
	global_load_dwordx4 v[224:227], v[76:77], off
	global_load_dwordx4 v[228:231], v[76:77], off offset:16
	global_load_dwordx4 v[238:241], v[78:79], off
	global_load_dwordx4 v[242:245], v[78:79], off offset:16
	s_waitcnt vmcnt(8)
	v_pk_add_f32 v[174:175], v[174:175], v[190:191]
	v_pk_add_f32 v[176:177], v[176:177], v[192:193]
	v_pk_add_f32 v[178:179], v[178:179], v[194:195]
	v_pk_add_f32 v[180:181], v[180:181], v[196:197]
	v_pk_add_f32 v[182:183], v[182:183], v[198:199]
	v_pk_add_f32 v[184:185], v[184:185], v[200:201]
	v_pk_add_f32 v[186:187], v[186:187], v[204:205]
	v_pk_add_f32 v[188:189], v[188:189], v[206:207]
	s_waitcnt vmcnt(4)
	v_pk_add_f32 v[174:175], v[174:175], v[208:209]
	v_pk_add_f32 v[176:177], v[176:177], v[210:211]
	v_pk_add_f32 v[178:179], v[178:179], v[212:213]
	v_pk_add_f32 v[180:181], v[180:181], v[214:215]
	v_pk_add_f32 v[182:183], v[182:183], v[216:217]
	v_pk_add_f32 v[184:185], v[184:185], v[218:219]
	v_pk_add_f32 v[186:187], v[186:187], v[220:221]
	v_pk_add_f32 v[188:189], v[188:189], v[222:223]
	s_waitcnt vmcnt(0)
	v_pk_fma_f32 v[44:45], v[174:175], v[224:225], v[44:45]
	v_pk_fma_f32 v[46:47], v[176:177], v[226:227], v[46:47]
	v_pk_fma_f32 v[42:43], v[178:179], v[228:229], v[42:43]
	v_pk_fma_f32 v[48:49], v[180:181], v[230:231], v[48:49]
	v_pk_fma_f32 v[38:39], v[182:183], v[238:239], v[38:39]
	v_pk_fma_f32 v[40:41], v[184:185], v[240:241], v[40:41]
	v_pk_fma_f32 v[32:33], v[186:187], v[242:243], v[32:33]
	v_pk_fma_f32 v[34:35], v[188:189], v[244:245], v[34:35]

.LBB0_1812:
	s_add_i32 s0, s75, s4
	s_cmpk_lt_i32 s0, 0x4200
	s_cselect_b32 s0, s0, s4
	s_ashr_i32 s1, s0, 31
	s_lshl_b64 s[0:1], s[0:1], 12
	v_lshl_add_u64 v[32:33], v[80:81], 0, s[0:1]
	global_load_dwordx4 v[46:49], v[32:33], off
	global_load_dwordx4 v[42:45], v[32:33], off offset:1024
	global_load_dwordx4 v[38:41], v[32:33], off offset:2048
	global_load_dwordx4 v[34:37], v[32:33], off offset:3072
	s_waitcnt vmcnt(8)
	s_andn2_b64 vcc, exec, s[8:9]
	s_cbranch_vccnz .LBB0_1802
	v_cvt_f32_f16_sdwa v167, v62 dst_sel:DWORD dst_unused:UNUSED_PAD src0_sel:WORD_1
	v_cvt_f32_f16_e32 v166, v62
	v_cvt_f32_f16_sdwa v163, v63 dst_sel:DWORD dst_unused:UNUSED_PAD src0_sel:WORD_1
	v_cvt_f32_f16_e32 v162, v63
	v_cvt_f32_f16_sdwa v161, v64 dst_sel:DWORD dst_unused:UNUSED_PAD src0_sel:WORD_1
	v_cvt_f32_f16_e32 v160, v64
	v_cvt_f32_f16_sdwa v165, v65 dst_sel:DWORD dst_unused:UNUSED_PAD src0_sel:WORD_1
	v_cvt_f32_f16_e32 v164, v65
	v_cvt_f32_f16_sdwa v155, v58 dst_sel:DWORD dst_unused:UNUSED_PAD src0_sel:WORD_1
	v_cvt_f32_f16_e32 v154, v58
	v_cvt_f32_f16_sdwa v157, v59 dst_sel:DWORD dst_unused:UNUSED_PAD src0_sel:WORD_1
	v_cvt_f32_f16_e32 v156, v59
	v_cvt_f32_f16_sdwa v153, v60 dst_sel:DWORD dst_unused:UNUSED_PAD src0_sel:WORD_1
	v_cvt_f32_f16_e32 v152, v60
	v_cvt_f32_f16_sdwa v159, v61 dst_sel:DWORD dst_unused:UNUSED_PAD src0_sel:WORD_1
	v_cvt_f32_f16_e32 v158, v61
	v_cvt_f32_f16_sdwa v61, v54 dst_sel:DWORD dst_unused:UNUSED_PAD src0_sel:WORD_1
	v_cvt_f32_f16_e32 v60, v54
	v_cvt_f32_f16_sdwa v63, v55 dst_sel:DWORD dst_unused:UNUSED_PAD src0_sel:WORD_1
	v_cvt_f32_f16_e32 v62, v55
	v_cvt_f32_f16_sdwa v59, v56 dst_sel:DWORD dst_unused:UNUSED_PAD src0_sel:WORD_1
	v_cvt_f32_f16_e32 v58, v56
	v_cvt_f32_f16_sdwa v65, v57 dst_sel:DWORD dst_unused:UNUSED_PAD src0_sel:WORD_1
	v_cvt_f32_f16_e32 v64, v57
	v_cvt_f32_f16_sdwa v55, v50 dst_sel:DWORD dst_unused:UNUSED_PAD src0_sel:WORD_1
	v_cvt_f32_f16_e32 v54, v50
	v_cvt_f32_f16_sdwa v57, v51 dst_sel:DWORD dst_unused:UNUSED_PAD src0_sel:WORD_1
	v_cvt_f32_f16_e32 v56, v51
	v_cvt_f32_f16_sdwa v33, v52 dst_sel:DWORD dst_unused:UNUSED_PAD src0_sel:WORD_1
	v_cvt_f32_f16_e32 v32, v52
	v_cvt_f32_f16_sdwa v51, v53 dst_sel:DWORD dst_unused:UNUSED_PAD src0_sel:WORD_1
	v_cvt_f32_f16_e32 v50, v53
	s_cmpk_gt_i32 s14, 0x3fff
	s_cselect_b64 s[2:3], -1, 0
	s_cmpk_lt_i32 s14, 0x4000
	s_cbranch_scc1 .LBB0_1815
	s_add_i32 s86, s14, 0xffffc000
	s_lshl_b64 s[0:1], s[86:87], 13
	v_lshl_add_u64 v[52:53], v[82:83], 0, s[0:1]
	global_load_dwordx4 v[190:193], v[52:53], off nt
	global_load_dwordx4 v[194:197], v[52:53], off offset:16 nt
	global_load_dwordx4 v[198:201], v[52:53], off offset:2048 nt
	global_load_dwordx4 v[204:207], v[52:53], off offset:2064 nt
	s_mov_b64 s[0:1], 0x400000
	v_lshl_add_u64 v[232:233], v[52:53], 0, s[0:1]
	global_load_dwordx4 v[208:211], v[232:233], off nt
	global_load_dwordx4 v[212:215], v[232:233], off offset:16 nt
	global_load_dwordx4 v[216:219], v[232:233], off offset:2048 nt
	global_load_dwordx4 v[220:223], v[232:233], off offset:2064 nt
	s_mov_b64 s[0:1], 0x800000
	v_lshl_add_u64 v[232:233], v[52:53], 0, s[0:1]
	global_load_dwordx4 v[224:227], v[232:233], off nt
	global_load_dwordx4 v[228:231], v[232:233], off offset:16 nt
	global_load_dwordx4 v[238:241], v[232:233], off offset:2048 nt
	global_load_dwordx4 v[242:245], v[232:233], off offset:2064 nt
	s_waitcnt vmcnt(8)
	v_mov_b64_e32 v[174:175], v[190:191]
	v_mov_b64_e32 v[176:177], v[192:193]
	v_mov_b64_e32 v[178:179], v[194:195]
	v_mov_b64_e32 v[180:181], v[196:197]
	v_mov_b64_e32 v[182:183], v[198:199]
	v_mov_b64_e32 v[184:185], v[200:201]
	v_mov_b64_e32 v[186:187], v[204:205]
	v_mov_b64_e32 v[188:189], v[206:207]
	s_mov_b64 s[0:1], 0xc00000
	v_lshl_add_u64 v[232:233], v[52:53], 0, s[0:1]
	global_load_dwordx4 v[190:193], v[232:233], off nt
	global_load_dwordx4 v[194:197], v[232:233], off offset:16 nt
	global_load_dwordx4 v[198:201], v[232:233], off offset:2048 nt
	global_load_dwordx4 v[204:207], v[232:233], off offset:2064 nt
	s_waitcnt vmcnt(8)
	v_pk_add_f32 v[174:175], v[174:175], v[208:209]
	v_pk_add_f32 v[176:177], v[176:177], v[210:211]
	v_pk_add_f32 v[178:179], v[178:179], v[212:213]
	v_pk_add_f32 v[180:181], v[180:181], v[214:215]
	v_pk_add_f32 v[182:183], v[182:183], v[216:217]
	v_pk_add_f32 v[184:185], v[184:185], v[218:219]
	v_pk_add_f32 v[186:187], v[186:187], v[220:221]
	v_pk_add_f32 v[188:189], v[188:189], v[222:223]
	s_mov_b64 s[0:1], 0x1000000
	v_lshl_add_u64 v[232:233], v[52:53], 0, s[0:1]
	global_load_dwordx4 v[208:211], v[232:233], off nt
	global_load_dwordx4 v[212:215], v[232:233], off offset:16 nt
	global_load_dwordx4 v[216:219], v[232:233], off offset:2048 nt
	global_load_dwordx4 v[220:223], v[232:233], off offset:2064 nt
	s_waitcnt vmcnt(8)
	v_pk_add_f32 v[174:175], v[174:175], v[224:225]
	v_pk_add_f32 v[176:177], v[176:177], v[226:227]
	v_pk_add_f32 v[178:179], v[178:179], v[228:229]
	v_pk_add_f32 v[180:181], v[180:181], v[230:231]
	v_pk_add_f32 v[182:183], v[182:183], v[238:239]
	v_pk_add_f32 v[184:185], v[184:185], v[240:241]
	v_pk_add_f32 v[186:187], v[186:187], v[242:243]
	v_pk_add_f32 v[188:189], v[188:189], v[244:245]
	s_mov_b64 s[0:1], 0x1400000
	v_lshl_add_u64 v[232:233], v[52:53], 0, s[0:1]
	global_load_dwordx4 v[224:227], v[232:233], off nt
	global_load_dwordx4 v[228:231], v[232:233], off offset:16 nt
	global_load_dwordx4 v[238:241], v[232:233], off offset:2048 nt
	global_load_dwordx4 v[242:245], v[232:233], off offset:2064 nt
	s_waitcnt vmcnt(8)
	v_pk_add_f32 v[174:175], v[174:175], v[190:191]
	v_pk_add_f32 v[176:177], v[176:177], v[192:193]
	v_pk_add_f32 v[178:179], v[178:179], v[194:195]
	v_pk_add_f32 v[180:181], v[180:181], v[196:197]
	v_pk_add_f32 v[182:183], v[182:183], v[198:199]
	v_pk_add_f32 v[184:185], v[184:185], v[200:201]
	v_pk_add_f32 v[186:187], v[186:187], v[204:205]
	v_pk_add_f32 v[188:189], v[188:189], v[206:207]
	s_mov_b64 s[0:1], 0x1800000
	v_lshl_add_u64 v[232:233], v[52:53], 0, s[0:1]
	global_load_dwordx4 v[190:193], v[232:233], off nt
	global_load_dwordx4 v[194:197], v[232:233], off offset:16 nt
	global_load_dwordx4 v[198:201], v[232:233], off offset:2048 nt
	global_load_dwordx4 v[204:207], v[232:233], off offset:2064 nt
	s_waitcnt vmcnt(8)
	v_pk_add_f32 v[174:175], v[174:175], v[208:209]
	v_pk_add_f32 v[176:177], v[176:177], v[210:211]
	v_pk_add_f32 v[178:179], v[178:179], v[212:213]
	v_pk_add_f32 v[180:181], v[180:181], v[214:215]
	v_pk_add_f32 v[182:183], v[182:183], v[216:217]
	v_pk_add_f32 v[184:185], v[184:185], v[218:219]
	v_pk_add_f32 v[186:187], v[186:187], v[220:221]
	v_pk_add_f32 v[188:189], v[188:189], v[222:223]
	s_mov_b64 s[0:1], 0x1c00000
	v_lshl_add_u64 v[232:233], v[52:53], 0, s[0:1]
	global_load_dwordx4 v[208:211], v[232:233], off nt
	global_load_dwordx4 v[212:215], v[232:233], off offset:16 nt
	global_load_dwordx4 v[216:219], v[232:233], off offset:2048 nt
	global_load_dwordx4 v[220:223], v[232:233], off offset:2064 nt
	s_waitcnt vmcnt(8)
	v_pk_add_f32 v[174:175], v[174:175], v[224:225]
	v_pk_add_f32 v[176:177], v[176:177], v[226:227]
	v_pk_add_f32 v[178:179], v[178:179], v[228:229]
	v_pk_add_f32 v[180:181], v[180:181], v[230:231]
	v_pk_add_f32 v[182:183], v[182:183], v[238:239]
	v_pk_add_f32 v[184:185], v[184:185], v[240:241]
	v_pk_add_f32 v[186:187], v[186:187], v[242:243]
	v_pk_add_f32 v[188:189], v[188:189], v[244:245]
	s_mov_b64 s[0:1], 0x2000000
	v_lshl_add_u64 v[232:233], v[52:53], 0, s[0:1]
	global_load_dwordx4 v[224:227], v[232:233], off nt
	global_load_dwordx4 v[228:231], v[232:233], off offset:16 nt
	global_load_dwordx4 v[238:241], v[232:233], off offset:2048 nt
	global_load_dwordx4 v[242:245], v[232:233], off offset:2064 nt
	s_waitcnt vmcnt(8)
	v_pk_add_f32 v[174:175], v[174:175], v[190:191]
	v_pk_add_f32 v[176:177], v[176:177], v[192:193]
	v_pk_add_f32 v[178:179], v[178:179], v[194:195]
	v_pk_add_f32 v[180:181], v[180:181], v[196:197]
	v_pk_add_f32 v[182:183], v[182:183], v[198:199]
	v_pk_add_f32 v[184:185], v[184:185], v[200:201]
	v_pk_add_f32 v[186:187], v[186:187], v[204:205]
	v_pk_add_f32 v[188:189], v[188:189], v[206:207]
	s_mov_b64 s[0:1], 0x2400000
	v_lshl_add_u64 v[232:233], v[52:53], 0, s[0:1]
	global_load_dwordx4 v[190:193], v[232:233], off nt
	global_load_dwordx4 v[194:197], v[232:233], off offset:16 nt
	global_load_dwordx4 v[198:201], v[232:233], off offset:2048 nt
	global_load_dwordx4 v[204:207], v[232:233], off offset:2064 nt
	s_waitcnt vmcnt(8)
	v_pk_add_f32 v[174:175], v[174:175], v[208:209]
	v_pk_add_f32 v[176:177], v[176:177], v[210:211]
	v_pk_add_f32 v[178:179], v[178:179], v[212:213]
	v_pk_add_f32 v[180:181], v[180:181], v[214:215]
	v_pk_add_f32 v[182:183], v[182:183], v[216:217]
	v_pk_add_f32 v[184:185], v[184:185], v[218:219]
	v_pk_add_f32 v[186:187], v[186:187], v[220:221]
	v_pk_add_f32 v[188:189], v[188:189], v[222:223]
	s_mov_b64 s[0:1], 0x2800000
	v_lshl_add_u64 v[232:233], v[52:53], 0, s[0:1]
	global_load_dwordx4 v[208:211], v[232:233], off nt
	global_load_dwordx4 v[212:215], v[232:233], off offset:16 nt
	global_load_dwordx4 v[216:219], v[232:233], off offset:2048 nt
	global_load_dwordx4 v[220:223], v[232:233], off offset:2064 nt
	s_waitcnt vmcnt(8)
	v_pk_add_f32 v[174:175], v[174:175], v[224:225]
	v_pk_add_f32 v[176:177], v[176:177], v[226:227]
	v_pk_add_f32 v[178:179], v[178:179], v[228:229]
	v_pk_add_f32 v[180:181], v[180:181], v[230:231]
	v_pk_add_f32 v[182:183], v[182:183], v[238:239]
	v_pk_add_f32 v[184:185], v[184:185], v[240:241]
	v_pk_add_f32 v[186:187], v[186:187], v[242:243]
	v_pk_add_f32 v[188:189], v[188:189], v[244:245]
	global_load_dwordx4 v[224:227], v[74:75], off
	global_load_dwordx4 v[228:231], v[74:75], off offset:16
	global_load_dwordx4 v[238:241], v[74:75], off offset:2048
	global_load_dwordx4 v[242:245], v[74:75], off offset:2064
	s_waitcnt vmcnt(8)
	v_pk_add_f32 v[174:175], v[174:175], v[190:191]
	v_pk_add_f32 v[176:177], v[176:177], v[192:193]
	v_pk_add_f32 v[178:179], v[178:179], v[194:195]
	v_pk_add_f32 v[180:181], v[180:181], v[196:197]
	v_pk_add_f32 v[182:183], v[182:183], v[198:199]
	v_pk_add_f32 v[184:185], v[184:185], v[200:201]
	v_pk_add_f32 v[186:187], v[186:187], v[204:205]
	v_pk_add_f32 v[188:189], v[188:189], v[206:207]
	s_mov_b64 s[0:1], 0x1000
	v_lshl_add_u64 v[232:233], v[52:53], 0, s[0:1]
	global_load_dwordx4 v[190:193], v[232:233], off nt
	global_load_dwordx4 v[194:197], v[232:233], off offset:16 nt
	global_load_dwordx4 v[198:201], v[232:233], off offset:2048 nt
	global_load_dwordx4 v[204:207], v[232:233], off offset:2064 nt
	s_waitcnt vmcnt(8)
	v_pk_add_f32 v[174:175], v[174:175], v[208:209]
	v_pk_add_f32 v[176:177], v[176:177], v[210:211]
	v_pk_add_f32 v[178:179], v[178:179], v[212:213]
	v_pk_add_f32 v[180:181], v[180:181], v[214:215]
	v_pk_add_f32 v[182:183], v[182:183], v[216:217]
	v_pk_add_f32 v[184:185], v[184:185], v[218:219]
	v_pk_add_f32 v[186:187], v[186:187], v[220:221]
	v_pk_add_f32 v[188:189], v[188:189], v[222:223]
	s_mov_b64 s[0:1], 0x401000
	v_lshl_add_u64 v[232:233], v[52:53], 0, s[0:1]
	global_load_dwordx4 v[208:211], v[232:233], off nt
	global_load_dwordx4 v[212:215], v[232:233], off offset:16 nt
	global_load_dwordx4 v[216:219], v[232:233], off offset:2048 nt
	global_load_dwordx4 v[220:223], v[232:233], off offset:2064 nt
	s_waitcnt vmcnt(8)
	v_pk_fma_f32 v[166:167], v[174:175], v[224:225], v[166:167]
	v_pk_fma_f32 v[162:163], v[176:177], v[226:227], v[162:163]
	v_pk_fma_f32 v[160:161], v[178:179], v[228:229], v[160:161]
	v_pk_fma_f32 v[164:165], v[180:181], v[230:231], v[164:165]
	v_pk_fma_f32 v[154:155], v[182:183], v[238:239], v[154:155]
	v_pk_fma_f32 v[156:157], v[184:185], v[240:241], v[156:157]
	v_pk_fma_f32 v[152:153], v[186:187], v[242:243], v[152:153]
	v_pk_fma_f32 v[158:159], v[188:189], v[244:245], v[158:159]
	s_mov_b64 s[0:1], 0x801000
	v_lshl_add_u64 v[232:233], v[52:53], 0, s[0:1]
	global_load_dwordx4 v[224:227], v[232:233], off nt
	global_load_dwordx4 v[228:231], v[232:233], off offset:16 nt
	global_load_dwordx4 v[238:241], v[232:233], off offset:2048 nt
	global_load_dwordx4 v[242:245], v[232:233], off offset:2064 nt
	s_waitcnt vmcnt(8)
	v_mov_b64_e32 v[174:175], v[190:191]
	v_mov_b64_e32 v[176:177], v[192:193]
	v_mov_b64_e32 v[178:179], v[194:195]
	v_mov_b64_e32 v[180:181], v[196:197]
	v_mov_b64_e32 v[182:183], v[198:199]
	v_mov_b64_e32 v[184:185], v[200:201]
	v_mov_b64_e32 v[186:187], v[204:205]
	v_mov_b64_e32 v[188:189], v[206:207]
	s_mov_b64 s[0:1], 0xc01000
	v_lshl_add_u64 v[232:233], v[52:53], 0, s[0:1]
	global_load_dwordx4 v[190:193], v[232:233], off nt
	global_load_dwordx4 v[194:197], v[232:233], off offset:16 nt
	global_load_dwordx4 v[198:201], v[232:233], off offset:2048 nt
	global_load_dwordx4 v[204:207], v[232:233], off offset:2064 nt
	s_waitcnt vmcnt(8)
	v_pk_add_f32 v[174:175], v[174:175], v[208:209]
	v_pk_add_f32 v[176:177], v[176:177], v[210:211]
	v_pk_add_f32 v[178:179], v[178:179], v[212:213]
	v_pk_add_f32 v[180:181], v[180:181], v[214:215]
	v_pk_add_f32 v[182:183], v[182:183], v[216:217]
	v_pk_add_f32 v[184:185], v[184:185], v[218:219]
	v_pk_add_f32 v[186:187], v[186:187], v[220:221]
	v_pk_add_f32 v[188:189], v[188:189], v[222:223]
	s_mov_b64 s[0:1], 0x1001000
	v_lshl_add_u64 v[232:233], v[52:53], 0, s[0:1]
	global_load_dwordx4 v[208:211], v[232:233], off nt
	global_load_dwordx4 v[212:215], v[232:233], off offset:16 nt
	global_load_dwordx4 v[216:219], v[232:233], off offset:2048 nt
	global_load_dwordx4 v[220:223], v[232:233], off offset:2064 nt
	s_waitcnt vmcnt(8)
	v_pk_add_f32 v[174:175], v[174:175], v[224:225]
	v_pk_add_f32 v[176:177], v[176:177], v[226:227]
	v_pk_add_f32 v[178:179], v[178:179], v[228:229]
	v_pk_add_f32 v[180:181], v[180:181], v[230:231]
	v_pk_add_f32 v[182:183], v[182:183], v[238:239]
	v_pk_add_f32 v[184:185], v[184:185], v[240:241]
	v_pk_add_f32 v[186:187], v[186:187], v[242:243]
	v_pk_add_f32 v[188:189], v[188:189], v[244:245]
	s_mov_b64 s[0:1], 0x1401000
	v_lshl_add_u64 v[232:233], v[52:53], 0, s[0:1]
	global_load_dwordx4 v[224:227], v[232:233], off nt
	global_load_dwordx4 v[228:231], v[232:233], off offset:16 nt
	global_load_dwordx4 v[238:241], v[232:233], off offset:2048 nt
	global_load_dwordx4 v[242:245], v[232:233], off offset:2064 nt
	s_waitcnt vmcnt(8)
	v_pk_add_f32 v[174:175], v[174:175], v[190:191]
	v_pk_add_f32 v[176:177], v[176:177], v[192:193]
	v_pk_add_f32 v[178:179], v[178:179], v[194:195]
	v_pk_add_f32 v[180:181], v[180:181], v[196:197]
	v_pk_add_f32 v[182:183], v[182:183], v[198:199]
	v_pk_add_f32 v[184:185], v[184:185], v[200:201]
	v_pk_add_f32 v[186:187], v[186:187], v[204:205]
	v_pk_add_f32 v[188:189], v[188:189], v[206:207]
	s_mov_b64 s[0:1], 0x1801000
	v_lshl_add_u64 v[232:233], v[52:53], 0, s[0:1]
	global_load_dwordx4 v[190:193], v[232:233], off nt
	global_load_dwordx4 v[194:197], v[232:233], off offset:16 nt
	global_load_dwordx4 v[198:201], v[232:233], off offset:2048 nt
	global_load_dwordx4 v[204:207], v[232:233], off offset:2064 nt
	s_waitcnt vmcnt(8)
	v_pk_add_f32 v[174:175], v[174:175], v[208:209]
	v_pk_add_f32 v[176:177], v[176:177], v[210:211]
	v_pk_add_f32 v[178:179], v[178:179], v[212:213]
	v_pk_add_f32 v[180:181], v[180:181], v[214:215]
	v_pk_add_f32 v[182:183], v[182:183], v[216:217]
	v_pk_add_f32 v[184:185], v[184:185], v[218:219]
	v_pk_add_f32 v[186:187], v[186:187], v[220:221]
	v_pk_add_f32 v[188:189], v[188:189], v[222:223]
	s_mov_b64 s[0:1], 0x1c01000
	v_lshl_add_u64 v[232:233], v[52:53], 0, s[0:1]
	global_load_dwordx4 v[208:211], v[232:233], off nt
	global_load_dwordx4 v[212:215], v[232:233], off offset:16 nt
	global_load_dwordx4 v[216:219], v[232:233], off offset:2048 nt
	global_load_dwordx4 v[220:223], v[232:233], off offset:2064 nt
	s_waitcnt vmcnt(8)
	v_pk_add_f32 v[174:175], v[174:175], v[224:225]
	v_pk_add_f32 v[176:177], v[176:177], v[226:227]
	v_pk_add_f32 v[178:179], v[178:179], v[228:229]
	v_pk_add_f32 v[180:181], v[180:181], v[230:231]
	v_pk_add_f32 v[182:183], v[182:183], v[238:239]
	v_pk_add_f32 v[184:185], v[184:185], v[240:241]
	v_pk_add_f32 v[186:187], v[186:187], v[242:243]
	v_pk_add_f32 v[188:189], v[188:189], v[244:245]
	s_mov_b64 s[0:1], 0x2001000
	v_lshl_add_u64 v[232:233], v[52:53], 0, s[0:1]
	global_load_dwordx4 v[224:227], v[232:233], off nt
	global_load_dwordx4 v[228:231], v[232:233], off offset:16 nt
	global_load_dwordx4 v[238:241], v[232:233], off offset:2048 nt
	global_load_dwordx4 v[242:245], v[232:233], off offset:2064 nt
	s_waitcnt vmcnt(8)
	v_pk_add_f32 v[174:175], v[174:175], v[190:191]
	v_pk_add_f32 v[176:177], v[176:177], v[192:193]
	v_pk_add_f32 v[178:179], v[178:179], v[194:195]
	v_pk_add_f32 v[180:181], v[180:181], v[196:197]
	v_pk_add_f32 v[182:183], v[182:183], v[198:199]
	v_pk_add_f32 v[184:185], v[184:185], v[200:201]
	v_pk_add_f32 v[186:187], v[186:187], v[204:205]
	v_pk_add_f32 v[188:189], v[188:189], v[206:207]
	s_mov_b64 s[0:1], 0x2401000
	v_lshl_add_u64 v[232:233], v[52:53], 0, s[0:1]
	global_load_dwordx4 v[190:193], v[232:233], off nt
	global_load_dwordx4 v[194:197], v[232:233], off offset:16 nt
	global_load_dwordx4 v[198:201], v[232:233], off offset:2048 nt
	global_load_dwordx4 v[204:207], v[232:233], off offset:2064 nt
	s_waitcnt vmcnt(8)
	v_pk_add_f32 v[174:175], v[174:175], v[208:209]
	v_pk_add_f32 v[176:177], v[176:177], v[210:211]
	v_pk_add_f32 v[178:179], v[178:179], v[212:213]
	v_pk_add_f32 v[180:181], v[180:181], v[214:215]
	v_pk_add_f32 v[182:183], v[182:183], v[216:217]
	v_pk_add_f32 v[184:185], v[184:185], v[218:219]
	v_pk_add_f32 v[186:187], v[186:187], v[220:221]
	v_pk_add_f32 v[188:189], v[188:189], v[222:223]
	s_mov_b64 s[0:1], 0x2801000
	v_lshl_add_u64 v[232:233], v[52:53], 0, s[0:1]
	global_load_dwordx4 v[208:211], v[232:233], off nt
	global_load_dwordx4 v[212:215], v[232:233], off offset:16 nt
	global_load_dwordx4 v[216:219], v[232:233], off offset:2048 nt
	global_load_dwordx4 v[220:223], v[232:233], off offset:2064 nt
	s_waitcnt vmcnt(8)
	v_pk_add_f32 v[174:175], v[174:175], v[224:225]
	v_pk_add_f32 v[176:177], v[176:177], v[226:227]
	v_pk_add_f32 v[178:179], v[178:179], v[228:229]
	v_pk_add_f32 v[180:181], v[180:181], v[230:231]
	v_pk_add_f32 v[182:183], v[182:183], v[238:239]
	v_pk_add_f32 v[184:185], v[184:185], v[240:241]
	v_pk_add_f32 v[186:187], v[186:187], v[242:243]
	v_pk_add_f32 v[188:189], v[188:189], v[244:245]
	global_load_dwordx4 v[224:227], v[76:77], off
	global_load_dwordx4 v[228:231], v[76:77], off offset:16
	global_load_dwordx4 v[238:241], v[78:79], off
	global_load_dwordx4 v[242:245], v[78:79], off offset:16
	s_waitcnt vmcnt(8)
	v_pk_add_f32 v[174:175], v[174:175], v[190:191]
	v_pk_add_f32 v[176:177], v[176:177], v[192:193]
	v_pk_add_f32 v[178:179], v[178:179], v[194:195]
	v_pk_add_f32 v[180:181], v[180:181], v[196:197]
	v_pk_add_f32 v[182:183], v[182:183], v[198:199]
	v_pk_add_f32 v[184:185], v[184:185], v[200:201]
	v_pk_add_f32 v[186:187], v[186:187], v[204:205]
	v_pk_add_f32 v[188:189], v[188:189], v[206:207]
	s_waitcnt vmcnt(4)
	v_pk_add_f32 v[174:175], v[174:175], v[208:209]
	v_pk_add_f32 v[176:177], v[176:177], v[210:211]
	v_pk_add_f32 v[178:179], v[178:179], v[212:213]
	v_pk_add_f32 v[180:181], v[180:181], v[214:215]
	v_pk_add_f32 v[182:183], v[182:183], v[216:217]
	v_pk_add_f32 v[184:185], v[184:185], v[218:219]
	v_pk_add_f32 v[186:187], v[186:187], v[220:221]
	v_pk_add_f32 v[188:189], v[188:189], v[222:223]
	s_waitcnt vmcnt(0)
	v_pk_fma_f32 v[60:61], v[174:175], v[224:225], v[60:61]
	v_pk_fma_f32 v[62:63], v[176:177], v[226:227], v[62:63]
	v_pk_fma_f32 v[58:59], v[178:179], v[228:229], v[58:59]
	v_pk_fma_f32 v[64:65], v[180:181], v[230:231], v[64:65]
	v_pk_fma_f32 v[54:55], v[182:183], v[238:239], v[54:55]
	v_pk_fma_f32 v[56:57], v[184:185], v[240:241], v[56:57]
	v_pk_fma_f32 v[32:33], v[186:187], v[242:243], v[32:33]
	v_pk_fma_f32 v[50:51], v[188:189], v[244:245], v[50:51]
